# s15 + lever 4 on the GEMM K-loops (G1a/G1b/G3): per-segment s_setprio flips deleted, one static s_setprio 1 for the trailing wave half per unit
# speedup vs baseline: 1.0071x; 1.0065x over previous
; #define PG8_STAGE(bufoff, gbase, voff) do { _Pragma("unroll") for (int _i = 0; _i < 2; ++_i) \
;         __builtin_amdgcn_global_load_lds((const unsigned*)((const char*)(gbase) + (voff)[_i]), (PG8_LAS unsigned*)(lds + (bufoff) + ldsw + _i * 8192), 16, 0, 0); } while (0)
; #define PG8_LDA(dst, b, h) do { _Pragma("unroll") for (int m = 0; m < 4; ++m) _Pragma("unroll") for (int k = 0; k < 2; ++k) dst[m][k] = *(const PG8_LAS bf16x8*)(lds + PG8_SA(b, h) + aoff + m * 2048 + k * 1024); } while (0)
; #define PG8_LDB(dst, b, h) do { _Pragma("unroll") for (int n = 0; n < 2; ++n) _Pragma("unroll") for (int k = 0; k < 2; ++k) dst[n][k] = *(const PG8_LAS bf16x8*)(lds + PG8_SB(b, h) + boff + n * 2048 + k * 1024); } while (0)
; #define PG8_WAIT_V(n) asm volatile("s_waitcnt vmcnt(" #n ")" ::: "memory")
; #define PG8_WAIT_L(n) asm volatile("s_waitcnt lgkmcnt(" #n ")" ::: "memory")
; #define PG8_BAR __builtin_amdgcn_s_barrier()
; #define PG8_SCHED __builtin_amdgcn_sched_barrier(0)
; template <class Epi, class Sched, bool ALIGN_EPI = false, bool SP2 = false, bool I8 = false>
; __device__ __forceinline__ void gemm_phase(PG8_LAS unsigned char* lds, const Gemm g, const Sched& S, const Epi& E, const int tid) {
;     ...
;     for (;;) {
;         const bool has_next = S.next(ui + 1, nxt);
;         const char* nA = has_next ? (const char*)g.A + (size_t)nxt.pm * tstepA : cA; const char* nB = has_next ? (const char*)g.Bt + (size_t)nxt.pn * tstepB : cB;
;         for (int t = 0; t < nt; t += 2) {
;             const bool last = (t == nt - 2);
;             const char* a1 = cA + (size_t)(t + 1) * kstep;
;             const char* a2 = last ? nA : cA + (size_t)(t + 2) * kstep; const char* b2 = last ? nB : cB + (size_t)(t + 2) * kstep;
;             const char* a3 = a2 + kstep; const char* b3 = b2 + kstep;
;             if (last && has_next) S.a_ready(nxt);
;             if constexpr (SP2) {
;             PG8_LDB(B0, 0, 0); PG8_LDB(B1, 0, 1); PG8_SCHED; PG8_LDA(At, 0, 0); PG8_STAGE(PG8_SA(1, 1), a1 + hstepA, voffA);
;             PG8_WAIT_V(8); PG8_WAIT_L(0); PG8_BAR; PG8_MMA(0, 0, At, B0); PG8_MMA(0, 1, At, B1); PG8_BAR; PG8_SCHED;
;     ...
;         for (int a = 0; a < 2; ++a)
; #pragma unroll
;             for (int b = 0; b < 2; ++b)
; #pragma unroll
;                 for (int m = 0; m < 4; ++m)
; #pragma unroll
;                     for (int n = 0; n < 2; ++n) acc[a][b][m][n] = AccT<I8>::zero();
.LBB0_269:
	s_ashr_i32 s29, s28, 31
	s_lshl_b64 s[30:31], s[28:29], 21
	s_add_u32 s30, s57, s30
	s_addc_u32 s31, s58, s31
	s_and_b64 s[36:37], s[34:35], exec
	s_cselect_b32 s11, s31, s41
	s_cselect_b32 s29, s30, s40
	s_ashr_i32 s27, s26, 31
	s_lshl_b64 s[36:37], s[26:27], 21
	s_add_u32 s36, s5, s36
	s_addc_u32 s37, s56, s37
	s_and_b64 s[46:47], s[34:35], exec
	s_cselect_b32 s27, s37, s39
	s_cselect_b32 s80, s36, s38
	s_add_u32 s85, s38, 0x100
	s_addc_u32 s86, s39, 0
	s_add_u32 s38, s40, 0x100080
	v_mov_b32_e32 v0, 0
	s_addc_u32 s39, s41, 0
	s_mov_b32 s87, -2
	v_mov_b32_e32 v1, v0
	v_mov_b32_e32 v2, v0
	v_mov_b32_e32 v3, v0
	v_mov_b32_e32 v4, v0
	v_mov_b32_e32 v5, v0
	v_mov_b32_e32 v6, v0
	v_mov_b32_e32 v7, v0
	v_mov_b32_e32 v8, v0
	v_mov_b32_e32 v9, v0
	v_mov_b32_e32 v10, v0
	v_mov_b32_e32 v11, v0
	v_mov_b32_e32 v12, v0
	v_mov_b32_e32 v13, v0
	v_mov_b32_e32 v14, v0
	v_mov_b32_e32 v15, v0
	v_mov_b32_e32 v24, v0
	v_mov_b32_e32 v25, v0
	v_mov_b32_e32 v26, v0
	v_mov_b32_e32 v27, v0
	v_mov_b32_e32 v28, v0
	v_mov_b32_e32 v29, v0
	v_mov_b32_e32 v30, v0
	v_mov_b32_e32 v31, v0
	v_mov_b32_e32 v40, v0
	v_mov_b32_e32 v41, v0
	v_mov_b32_e32 v42, v0
	v_mov_b32_e32 v43, v0
	v_mov_b32_e32 v44, v0
	v_mov_b32_e32 v45, v0
	v_mov_b32_e32 v46, v0
	v_mov_b32_e32 v47, v0
	v_mov_b32_e32 v16, v0
	v_mov_b32_e32 v17, v0
	v_mov_b32_e32 v18, v0
	v_mov_b32_e32 v19, v0
	v_mov_b32_e32 v20, v0
	v_mov_b32_e32 v21, v0
	v_mov_b32_e32 v22, v0
	v_mov_b32_e32 v23, v0
	v_mov_b32_e32 v32, v0
	v_mov_b32_e32 v33, v0
	v_mov_b32_e32 v34, v0
	v_mov_b32_e32 v35, v0
	v_mov_b32_e32 v36, v0
	v_mov_b32_e32 v37, v0
	v_mov_b32_e32 v38, v0
	v_mov_b32_e32 v39, v0
	v_mov_b32_e32 v48, v0
	v_mov_b32_e32 v49, v0
	v_mov_b32_e32 v50, v0
	v_mov_b32_e32 v51, v0
	v_mov_b32_e32 v52, v0
	v_mov_b32_e32 v53, v0
	v_mov_b32_e32 v54, v0
	v_mov_b32_e32 v55, v0
	v_mov_b32_e32 v56, v0
	v_mov_b32_e32 v57, v0
	v_mov_b32_e32 v58, v0
	v_mov_b32_e32 v59, v0
	v_mov_b32_e32 v60, v0
	v_mov_b32_e32 v61, v0
	v_mov_b32_e32 v62, v0
	v_mov_b32_e32 v63, v0
	v_mov_b32_e32 v64, v0
	v_mov_b32_e32 v65, v0
	v_mov_b32_e32 v66, v0
	v_mov_b32_e32 v67, v0
	v_mov_b32_e32 v68, v0
	v_mov_b32_e32 v69, v0
	v_mov_b32_e32 v70, v0
	v_mov_b32_e32 v71, v0
	v_mov_b32_e32 v72, v0
	v_mov_b32_e32 v73, v0
	v_mov_b32_e32 v74, v0
	v_mov_b32_e32 v75, v0
	v_mov_b32_e32 v76, v0
	v_mov_b32_e32 v77, v0
	v_mov_b32_e32 v78, v0
	v_mov_b32_e32 v79, v0
	v_mov_b32_e32 v88, v0
	v_mov_b32_e32 v89, v0
	v_mov_b32_e32 v90, v0
	v_mov_b32_e32 v91, v0
	v_mov_b32_e32 v92, v0
	v_mov_b32_e32 v93, v0
	v_mov_b32_e32 v94, v0
	v_mov_b32_e32 v95, v0
	v_mov_b32_e32 v106, v0
	v_mov_b32_e32 v107, v0
	v_mov_b32_e32 v108, v0
	v_mov_b32_e32 v109, v0
	v_mov_b32_e32 v110, v0
	v_mov_b32_e32 v111, v0
	v_mov_b32_e32 v112, v0
	v_mov_b32_e32 v113, v0
	v_mov_b32_e32 v80, v0
	v_mov_b32_e32 v81, v0
	v_mov_b32_e32 v82, v0
	v_mov_b32_e32 v83, v0
	v_mov_b32_e32 v84, v0
	v_mov_b32_e32 v85, v0
	v_mov_b32_e32 v86, v0
	v_mov_b32_e32 v87, v0
	v_mov_b32_e32 v98, v0
	v_mov_b32_e32 v99, v0
	v_mov_b32_e32 v100, v0
	v_mov_b32_e32 v101, v0
	v_mov_b32_e32 v102, v0
	v_mov_b32_e32 v103, v0
	v_mov_b32_e32 v104, v0
	v_mov_b32_e32 v105, v0
	v_mov_b32_e32 v114, v0
	v_mov_b32_e32 v115, v0
	v_mov_b32_e32 v116, v0
	v_mov_b32_e32 v117, v0
	v_mov_b32_e32 v118, v0
	v_mov_b32_e32 v119, v0
	v_mov_b32_e32 v120, v0
	v_mov_b32_e32 v121, v0
	v_mov_b32_e32 v122, v0
	v_mov_b32_e32 v123, v0
	v_mov_b32_e32 v124, v0
	v_mov_b32_e32 v125, v0
	v_mov_b32_e32 v126, v0
	v_mov_b32_e32 v127, v0
	v_mov_b32_e32 v128, v0
	v_mov_b32_e32 v129, v0
	s_cmp_lg_u64 s[22:23], 0
	s_cbranch_scc1 .Lgprio_270
	s_setprio 1
.Lgprio_270:
.LBB0_270:
	s_add_u32 s40, s38, 0xfff00080
	s_addc_u32 s41, s39, -1
	s_add_i32 s88, 0, 0x10000
	s_cmp_eq_u32 s87, 60
	s_cselect_b32 s47, s11, s41
	s_cselect_b32 s46, s29, s40
	s_cselect_b32 s41, s27, s86
	s_cselect_b32 s40, s80, s85
	s_add_i32 s90, 0, 0x14000
	v_add_u32_e32 v156, s88, v141
	v_add_u32_e32 v172, s90, v141
	ds_read_b128 v[144:147], v156
	ds_read_b128 v[148:151], v156 offset:1024
	ds_read_b128 v[152:155], v156 offset:2048
	ds_read_b128 v[156:159], v156 offset:3072
	ds_read_b128 v[160:163], v172
	ds_read_b128 v[164:167], v172 offset:1024
	ds_read_b128 v[168:171], v172 offset:2048
	ds_read_b128 v[172:175], v172 offset:3072
	v_lshl_add_u64 v[212:213], s[38:39], 0, v[138:139]
	s_add_i32 m0, s13, 0xc000
	ds_read_b128 v[176:179], v143
	ds_read_b128 v[180:183], v143 offset:1024
	ds_read_b128 v[184:187], v143 offset:2048
	ds_read_b128 v[188:191], v143 offset:3072
	ds_read_b128 v[192:195], v143 offset:4096
	ds_read_b128 v[200:203], v143 offset:5120
	ds_read_b128 v[204:207], v143 offset:6144
	ds_read_b128 v[208:211], v143 offset:7168
	global_load_lds_dwordx4 v[212:213], off
	v_lshl_add_u64 v[212:213], s[38:39], 0, v[136:137]
	s_add_i32 m0, s13, 0xe000
	s_nop 0
	global_load_lds_dwordx4 v[212:213], off
	s_waitcnt vmcnt(8)
	s_waitcnt lgkmcnt(0)
	s_barrier
; #define PG8_STAGE(bufoff, gbase, voff) do { _Pragma("unroll") for (int _i = 0; _i < 2; ++_i) \
;         __builtin_amdgcn_global_load_lds((const unsigned*)((const char*)(gbase) + (voff)[_i]), (PG8_LAS unsigned*)(lds + (bufoff) + ldsw + _i * 8192), 16, 0, 0); } while (0)
; #define PG8_LDA(dst, b, h) do { _Pragma("unroll") for (int m = 0; m < 4; ++m) _Pragma("unroll") for (int k = 0; k < 2; ++k) dst[m][k] = *(const PG8_LAS bf16x8*)(lds + PG8_SA(b, h) + aoff + m * 2048 + k * 1024); } while (0)
; #define PG8_LDB(dst, b, h) do { _Pragma("unroll") for (int n = 0; n < 2; ++n) _Pragma("unroll") for (int k = 0; k < 2; ++k) dst[n][k] = *(const PG8_LAS bf16x8*)(lds + PG8_SB(b, h) + boff + n * 2048 + k * 1024); } while (0)
; #define PG8_MMA(ai, bj, At, Bt) do { __builtin_amdgcn_s_setprio(1); _Pragma("unroll") for (int m = 0; m < 4; ++m) _Pragma("unroll") for (int n = 0; n < 2; ++n) _Pragma("unroll") for (int k = 0; k < 2; ++k) \
;         mma1<I8>(acc[ai][bj][m][n], Bt[n][k], At[m][k]); __builtin_amdgcn_s_setprio(0); } while (0)
; #define PG8_WAIT_V(n) asm volatile("s_waitcnt vmcnt(" #n ")" ::: "memory")
; #define PG8_WAIT_L(n) asm volatile("s_waitcnt lgkmcnt(" #n ")" ::: "memory")
; #define PG8_BAR __builtin_amdgcn_s_barrier()
; #define PG8_SCHED __builtin_amdgcn_sched_barrier(0)
; template <class Epi, class Sched, bool ALIGN_EPI = false, bool SP2 = false, bool I8 = false>
; __device__ __forceinline__ void gemm_phase(PG8_LAS unsigned char* lds, const Gemm g, const Sched& S, const Epi& E, const int tid) {
;     ...
;             PG8_LDB(B0, 0, 0); PG8_LDB(B1, 0, 1); PG8_SCHED; PG8_LDA(At, 0, 0); PG8_STAGE(PG8_SA(1, 1), a1 + hstepA, voffA);
;             PG8_WAIT_V(8); PG8_WAIT_L(0); PG8_BAR; PG8_MMA(0, 0, At, B0); PG8_MMA(0, 1, At, B1); PG8_BAR; PG8_SCHED;
;             PG8_LDA(At, 0, 1); PG8_STAGE(PG8_SB(0, 0), b2, voffB); PG8_STAGE(PG8_SB(0, 1), b2 + hstepB, voffB); PG8_STAGE(PG8_SA(0, 0), a2, voffA);
;             PG8_WAIT_V(8); PG8_WAIT_L(0); PG8_BAR; PG8_MMA(1, 0, At, B0); PG8_MMA(1, 1, At, B1); PG8_BAR; PG8_SCHED;
	s_waitcnt lgkmcnt(0)
	v_mfma_f32_16x16x32_bf16 v[126:129], v[144:147], v[176:179], v[126:129]
	v_mfma_f32_16x16x32_bf16 v[122:125], v[152:155], v[176:179], v[122:125]
	v_mfma_f32_16x16x32_bf16 v[118:121], v[144:147], v[184:187], v[118:121]
	v_mfma_f32_16x16x32_bf16 v[114:117], v[152:155], v[184:187], v[114:117]
	v_mfma_f32_16x16x32_bf16 v[102:105], v[144:147], v[192:195], v[102:105]
	v_mfma_f32_16x16x32_bf16 v[98:101], v[152:155], v[192:195], v[98:101]
	v_mfma_f32_16x16x32_bf16 v[84:87], v[144:147], v[204:207], v[84:87]
	v_mfma_f32_16x16x32_bf16 v[80:83], v[152:155], v[204:207], v[80:83]
	v_mfma_f32_16x16x32_bf16 v[126:129], v[148:151], v[180:183], v[126:129]
	v_mfma_f32_16x16x32_bf16 v[122:125], v[156:159], v[180:183], v[122:125]
	v_mfma_f32_16x16x32_bf16 v[118:121], v[148:151], v[188:191], v[118:121]
	v_mfma_f32_16x16x32_bf16 v[114:117], v[156:159], v[188:191], v[114:117]
	v_mfma_f32_16x16x32_bf16 v[102:105], v[148:151], v[200:203], v[102:105]
	v_mfma_f32_16x16x32_bf16 v[98:101], v[156:159], v[200:203], v[98:101]
	v_mfma_f32_16x16x32_bf16 v[84:87], v[148:151], v[208:211], v[84:87]
	v_mfma_f32_16x16x32_bf16 v[80:83], v[156:159], v[208:211], v[80:83]
	v_mfma_f32_16x16x32_bf16 v[110:113], v[160:163], v[176:179], v[110:113]
	v_mfma_f32_16x16x32_bf16 v[106:109], v[168:171], v[176:179], v[106:109]
	v_mfma_f32_16x16x32_bf16 v[92:95], v[160:163], v[184:187], v[92:95]
	v_mfma_f32_16x16x32_bf16 v[88:91], v[168:171], v[184:187], v[88:91]
	v_mfma_f32_16x16x32_bf16 v[76:79], v[160:163], v[192:195], v[76:79]
	v_mfma_f32_16x16x32_bf16 v[72:75], v[168:171], v[192:195], v[72:75]
	v_mfma_f32_16x16x32_bf16 v[68:71], v[160:163], v[204:207], v[68:71]
	v_mfma_f32_16x16x32_bf16 v[64:67], v[168:171], v[204:207], v[64:67]
	v_mfma_f32_16x16x32_bf16 v[110:113], v[164:167], v[180:183], v[110:113]
	v_mfma_f32_16x16x32_bf16 v[106:109], v[172:175], v[180:183], v[106:109]
	v_mfma_f32_16x16x32_bf16 v[92:95], v[164:167], v[188:191], v[92:95]
	v_mfma_f32_16x16x32_bf16 v[88:91], v[172:175], v[188:191], v[88:91]
	v_mfma_f32_16x16x32_bf16 v[76:79], v[164:167], v[200:203], v[76:79]
	v_mfma_f32_16x16x32_bf16 v[72:75], v[172:175], v[200:203], v[72:75]
	v_mfma_f32_16x16x32_bf16 v[68:71], v[164:167], v[208:211], v[68:71]
	v_mfma_f32_16x16x32_bf16 v[64:67], v[172:175], v[208:211], v[64:67]
	s_barrier
	s_add_i32 s88, s88, s59
	v_lshl_add_u64 v[212:213], s[40:41], 0, v[96:97]
	s_mov_b32 m0, s88
	ds_read_b128 v[176:179], v143 offset:16384
	ds_read_b128 v[180:183], v143 offset:17408
	ds_read_b128 v[184:187], v143 offset:18432
	ds_read_b128 v[188:191], v143 offset:19456
	ds_read_b128 v[192:195], v143 offset:20480
	ds_read_b128 v[200:203], v143 offset:21504
	ds_read_b128 v[204:207], v143 offset:22528
	ds_read_b128 v[208:211], v143 offset:23552
	global_load_lds_dwordx4 v[212:213], off
	s_add_i32 m0, s88, 0x2000
	s_add_u32 s88, s40, 0x100000
	v_lshl_add_u64 v[214:215], s[40:41], 0, v[134:135]
	s_addc_u32 s89, s41, 0
	s_add_i32 s90, s90, s59
	global_load_lds_dwordx4 v[214:215], off
	v_lshl_add_u64 v[216:217], s[88:89], 0, v[96:97]
	s_mov_b32 m0, s90
	v_lshl_add_u64 v[218:219], s[46:47], 0, v[132:133]
	global_load_lds_dwordx4 v[216:217], off
	v_lshl_add_u64 v[216:217], s[88:89], 0, v[134:135]
	s_add_i32 m0, s90, 0x2000
	s_nop 0
	global_load_lds_dwordx4 v[216:217], off
	v_lshl_add_u64 v[216:217], s[46:47], 0, v[130:131]
	s_mov_b32 m0, s13
	s_nop 0
	global_load_lds_dwordx4 v[216:217], off
	s_mov_b32 m0, s60
	s_nop 0
	global_load_lds_dwordx4 v[218:219], off
	s_waitcnt vmcnt(8)
	s_waitcnt lgkmcnt(0)
	s_barrier
	s_waitcnt lgkmcnt(0)
	v_mfma_f32_16x16x32_bf16 v[60:63], v[144:147], v[176:179], v[60:63]
	v_mfma_f32_16x16x32_bf16 v[56:59], v[152:155], v[176:179], v[56:59]
	v_mfma_f32_16x16x32_bf16 v[52:55], v[144:147], v[184:187], v[52:55]
	v_mfma_f32_16x16x32_bf16 v[48:51], v[152:155], v[184:187], v[48:51]
	v_mfma_f32_16x16x32_bf16 v[36:39], v[144:147], v[192:195], v[36:39]
	v_mfma_f32_16x16x32_bf16 v[32:35], v[152:155], v[192:195], v[32:35]
	v_mfma_f32_16x16x32_bf16 v[20:23], v[144:147], v[204:207], v[20:23]
	v_mfma_f32_16x16x32_bf16 v[16:19], v[152:155], v[204:207], v[16:19]
	v_mfma_f32_16x16x32_bf16 v[60:63], v[148:151], v[180:183], v[60:63]
	v_mfma_f32_16x16x32_bf16 v[56:59], v[156:159], v[180:183], v[56:59]
	v_mfma_f32_16x16x32_bf16 v[52:55], v[148:151], v[188:191], v[52:55]
	v_mfma_f32_16x16x32_bf16 v[48:51], v[156:159], v[188:191], v[48:51]
	v_mfma_f32_16x16x32_bf16 v[36:39], v[148:151], v[200:203], v[36:39]
	v_mfma_f32_16x16x32_bf16 v[32:35], v[156:159], v[200:203], v[32:35]
	v_mfma_f32_16x16x32_bf16 v[20:23], v[148:151], v[208:211], v[20:23]
	v_mfma_f32_16x16x32_bf16 v[16:19], v[156:159], v[208:211], v[16:19]
	v_mfma_f32_16x16x32_bf16 v[44:47], v[160:163], v[176:179], v[44:47]
	v_mfma_f32_16x16x32_bf16 v[40:43], v[168:171], v[176:179], v[40:43]
	v_mfma_f32_16x16x32_bf16 v[28:31], v[160:163], v[184:187], v[28:31]
	v_mfma_f32_16x16x32_bf16 v[24:27], v[168:171], v[184:187], v[24:27]
	v_mfma_f32_16x16x32_bf16 v[12:15], v[160:163], v[192:195], v[12:15]
	v_mfma_f32_16x16x32_bf16 v[8:11], v[168:171], v[192:195], v[8:11]
	v_mfma_f32_16x16x32_bf16 v[4:7], v[160:163], v[204:207], v[4:7]
	v_mfma_f32_16x16x32_bf16 v[0:3], v[168:171], v[204:207], v[0:3]
	v_mfma_f32_16x16x32_bf16 v[44:47], v[164:167], v[180:183], v[44:47]
	v_mfma_f32_16x16x32_bf16 v[40:43], v[172:175], v[180:183], v[40:43]
	v_mfma_f32_16x16x32_bf16 v[28:31], v[164:167], v[188:191], v[28:31]
	v_mfma_f32_16x16x32_bf16 v[24:27], v[172:175], v[188:191], v[24:27]
	v_mfma_f32_16x16x32_bf16 v[12:15], v[164:167], v[200:203], v[12:15]
	v_mfma_f32_16x16x32_bf16 v[8:11], v[172:175], v[200:203], v[8:11]
	v_mfma_f32_16x16x32_bf16 v[4:7], v[164:167], v[208:211], v[4:7]
	v_mfma_f32_16x16x32_bf16 v[0:3], v[172:175], v[208:211], v[0:3]
	s_barrier
; #define PG8_STAGE(bufoff, gbase, voff) do { _Pragma("unroll") for (int _i = 0; _i < 2; ++_i) \
;         __builtin_amdgcn_global_load_lds((const unsigned*)((const char*)(gbase) + (voff)[_i]), (PG8_LAS unsigned*)(lds + (bufoff) + ldsw + _i * 8192), 16, 0, 0); } while (0)
; #define PG8_LDA(dst, b, h) do { _Pragma("unroll") for (int m = 0; m < 4; ++m) _Pragma("unroll") for (int k = 0; k < 2; ++k) dst[m][k] = *(const PG8_LAS bf16x8*)(lds + PG8_SA(b, h) + aoff + m * 2048 + k * 1024); } while (0)
; #define PG8_LDB(dst, b, h) do { _Pragma("unroll") for (int n = 0; n < 2; ++n) _Pragma("unroll") for (int k = 0; k < 2; ++k) dst[n][k] = *(const PG8_LAS bf16x8*)(lds + PG8_SB(b, h) + boff + n * 2048 + k * 1024); } while (0)
; #define PG8_MMA(ai, bj, At, Bt) do { __builtin_amdgcn_s_setprio(1); _Pragma("unroll") for (int m = 0; m < 4; ++m) _Pragma("unroll") for (int n = 0; n < 2; ++n) _Pragma("unroll") for (int k = 0; k < 2; ++k) \
;         mma1<I8>(acc[ai][bj][m][n], Bt[n][k], At[m][k]); __builtin_amdgcn_s_setprio(0); } while (0)
; #define PG8_WAIT_V(n) asm volatile("s_waitcnt vmcnt(" #n ")" ::: "memory")
; #define PG8_WAIT_L(n) asm volatile("s_waitcnt lgkmcnt(" #n ")" ::: "memory")
; #define PG8_BAR __builtin_amdgcn_s_barrier()
; #define PG8_SCHED __builtin_amdgcn_sched_barrier(0)
; template <class Epi, class Sched, bool ALIGN_EPI = false, bool SP2 = false, bool I8 = false>
; __device__ __forceinline__ void gemm_phase(PG8_LAS unsigned char* lds, const Gemm g, const Sched& S, const Epi& E, const int tid) {
;     ...
;             PG8_LDB(B0, 1, 0); PG8_LDB(B1, 1, 1); PG8_SCHED; PG8_LDA(At, 1, 0); PG8_STAGE(PG8_SA(0, 1), a2 + hstepA, voffA);
;             PG8_WAIT_V(8); PG8_WAIT_L(0); PG8_BAR; PG8_MMA(0, 0, At, B0); PG8_MMA(0, 1, At, B1); PG8_BAR; PG8_SCHED;
	s_add_i32 s88, 0, 0x18000
	s_add_i32 s89, 0, 0x1c000
	v_add_u32_e32 v156, s88, v141
	v_add_u32_e32 v172, s89, v141
	ds_read_b128 v[144:147], v156
	ds_read_b128 v[148:151], v156 offset:1024
	ds_read_b128 v[152:155], v156 offset:2048
	ds_read_b128 v[156:159], v156 offset:3072
	ds_read_b128 v[160:163], v172
	ds_read_b128 v[164:167], v172 offset:1024
	ds_read_b128 v[168:171], v172 offset:2048
	ds_read_b128 v[172:175], v172 offset:3072
	s_add_u32 s46, s46, 0x100000
	s_addc_u32 s47, s47, 0
	s_mov_b32 m0, s62
	v_lshl_add_u64 v[220:221], s[46:47], 0, v[130:131]
	ds_read_b128 v[176:179], v143 offset:32768
	ds_read_b128 v[180:183], v143 offset:33792
	ds_read_b128 v[184:187], v143 offset:34816
	ds_read_b128 v[188:191], v143 offset:35840
	ds_read_b128 v[192:195], v143 offset:36864
	ds_read_b128 v[200:203], v143 offset:37888
	ds_read_b128 v[204:207], v143 offset:38912
	ds_read_b128 v[208:211], v143 offset:39936
	global_load_lds_dwordx4 v[220:221], off
	v_lshl_add_u64 v[220:221], s[46:47], 0, v[132:133]
	s_mov_b32 m0, s63
	s_nop 0
	global_load_lds_dwordx4 v[220:221], off
	s_waitcnt vmcnt(8)
	s_waitcnt lgkmcnt(0)
	s_barrier
	s_waitcnt lgkmcnt(0)
	v_mfma_f32_16x16x32_bf16 v[126:129], v[144:147], v[176:179], v[126:129]
	v_mfma_f32_16x16x32_bf16 v[122:125], v[152:155], v[176:179], v[122:125]
	v_mfma_f32_16x16x32_bf16 v[118:121], v[144:147], v[184:187], v[118:121]
	v_mfma_f32_16x16x32_bf16 v[114:117], v[152:155], v[184:187], v[114:117]
	v_mfma_f32_16x16x32_bf16 v[102:105], v[144:147], v[192:195], v[102:105]
	v_mfma_f32_16x16x32_bf16 v[98:101], v[152:155], v[192:195], v[98:101]
	v_mfma_f32_16x16x32_bf16 v[84:87], v[144:147], v[204:207], v[84:87]
	v_mfma_f32_16x16x32_bf16 v[80:83], v[152:155], v[204:207], v[80:83]
	v_mfma_f32_16x16x32_bf16 v[126:129], v[148:151], v[180:183], v[126:129]
	v_mfma_f32_16x16x32_bf16 v[122:125], v[156:159], v[180:183], v[122:125]
	v_mfma_f32_16x16x32_bf16 v[118:121], v[148:151], v[188:191], v[118:121]
	v_mfma_f32_16x16x32_bf16 v[114:117], v[156:159], v[188:191], v[114:117]
	v_mfma_f32_16x16x32_bf16 v[102:105], v[148:151], v[200:203], v[102:105]
	v_mfma_f32_16x16x32_bf16 v[98:101], v[156:159], v[200:203], v[98:101]
	v_mfma_f32_16x16x32_bf16 v[84:87], v[148:151], v[208:211], v[84:87]
	v_mfma_f32_16x16x32_bf16 v[80:83], v[156:159], v[208:211], v[80:83]
	v_mfma_f32_16x16x32_bf16 v[110:113], v[160:163], v[176:179], v[110:113]
	v_mfma_f32_16x16x32_bf16 v[106:109], v[168:171], v[176:179], v[106:109]
	v_mfma_f32_16x16x32_bf16 v[92:95], v[160:163], v[184:187], v[92:95]
	v_mfma_f32_16x16x32_bf16 v[88:91], v[168:171], v[184:187], v[88:91]
	v_mfma_f32_16x16x32_bf16 v[76:79], v[160:163], v[192:195], v[76:79]
	v_mfma_f32_16x16x32_bf16 v[72:75], v[168:171], v[192:195], v[72:75]
	v_mfma_f32_16x16x32_bf16 v[68:71], v[160:163], v[204:207], v[68:71]
	v_mfma_f32_16x16x32_bf16 v[64:67], v[168:171], v[204:207], v[64:67]
	v_mfma_f32_16x16x32_bf16 v[110:113], v[164:167], v[180:183], v[110:113]
	v_mfma_f32_16x16x32_bf16 v[106:109], v[172:175], v[180:183], v[106:109]
	v_mfma_f32_16x16x32_bf16 v[92:95], v[164:167], v[188:191], v[92:95]
	v_mfma_f32_16x16x32_bf16 v[88:91], v[172:175], v[188:191], v[88:91]
	v_mfma_f32_16x16x32_bf16 v[76:79], v[164:167], v[200:203], v[76:79]
	v_mfma_f32_16x16x32_bf16 v[72:75], v[172:175], v[200:203], v[72:75]
	v_mfma_f32_16x16x32_bf16 v[68:71], v[164:167], v[208:211], v[68:71]
	v_mfma_f32_16x16x32_bf16 v[64:67], v[172:175], v[208:211], v[64:67]
	s_barrier
; #define PG8_STAGE(bufoff, gbase, voff) do { _Pragma("unroll") for (int _i = 0; _i < 2; ++_i) \
;         __builtin_amdgcn_global_load_lds((const unsigned*)((const char*)(gbase) + (voff)[_i]), (PG8_LAS unsigned*)(lds + (bufoff) + ldsw + _i * 8192), 16, 0, 0); } while (0)
; #define PG8_LDA(dst, b, h) do { _Pragma("unroll") for (int m = 0; m < 4; ++m) _Pragma("unroll") for (int k = 0; k < 2; ++k) dst[m][k] = *(const PG8_LAS bf16x8*)(lds + PG8_SA(b, h) + aoff + m * 2048 + k * 1024); } while (0)
; #define PG8_MMA(ai, bj, At, Bt) do { __builtin_amdgcn_s_setprio(1); _Pragma("unroll") for (int m = 0; m < 4; ++m) _Pragma("unroll") for (int n = 0; n < 2; ++n) _Pragma("unroll") for (int k = 0; k < 2; ++k) \
;         mma1<I8>(acc[ai][bj][m][n], Bt[n][k], At[m][k]); __builtin_amdgcn_s_setprio(0); } while (0)
; #define PG8_WAIT_V(n) asm volatile("s_waitcnt vmcnt(" #n ")" ::: "memory")
; #define PG8_WAIT_L(n) asm volatile("s_waitcnt lgkmcnt(" #n ")" ::: "memory")
; #define PG8_BAR __builtin_amdgcn_s_barrier()
; #define PG8_SCHED __builtin_amdgcn_sched_barrier(0)
; template <class Epi, class Sched, bool ALIGN_EPI = false, bool SP2 = false, bool I8 = false>
; __device__ __forceinline__ void gemm_phase(PG8_LAS unsigned char* lds, const Gemm g, const Sched& S, const Epi& E, const int tid) {
;     ...
;             PG8_LDA(At, 1, 1); PG8_STAGE(PG8_SB(1, 0), b3, voffB); PG8_STAGE(PG8_SB(1, 1), b3 + hstepB, voffB); PG8_STAGE(PG8_SA(1, 0), a3, voffA);
;             PG8_WAIT_V(8); PG8_WAIT_L(0); PG8_BAR; PG8_MMA(1, 0, At, B0); PG8_MMA(1, 1, At, B1); PG8_BAR; PG8_SCHED;
;             if constexpr (HasMid<Epi>::value) { if (t + 2 == Epi::SEAM0 || t + 2 == Epi::SEAM1) E.mid(acc, cur, t + 2 == Epi::SEAM0 ? 0 : 1, wr, wc, fr, fq); }
;     ...
;         if constexpr (ALIGN_EPI) { if (wr == 0) PG8_BAR; }
;         if constexpr (!Epi::AFTER_DRAIN) { E(acc, cur, wr, wc, fr, fq); S.done(cur); }
	s_add_i32 s46, s88, s59
	v_lshl_add_u64 v[212:213], v[212:213], 0, s[42:43]
	s_mov_b32 m0, s46
	ds_read_b128 v[176:179], v143 offset:49152
	ds_read_b128 v[180:183], v143 offset:50176
	ds_read_b128 v[184:187], v143 offset:51200
	ds_read_b128 v[188:191], v143 offset:52224
	ds_read_b128 v[192:195], v143 offset:53248
	ds_read_b128 v[200:203], v143 offset:54272
	ds_read_b128 v[204:207], v143 offset:55296
	ds_read_b128 v[208:211], v143 offset:56320
	global_load_lds_dwordx4 v[212:213], off
	s_add_i32 m0, s46, 0x2000
	s_add_u32 s40, s40, 0x100080
	v_lshl_add_u64 v[212:213], v[214:215], 0, s[42:43]
	s_addc_u32 s41, s41, 0
	s_add_i32 s46, s89, s59
	global_load_lds_dwordx4 v[212:213], off
	v_lshl_add_u64 v[212:213], s[40:41], 0, v[96:97]
	s_mov_b32 m0, s46
	s_nop 0
	global_load_lds_dwordx4 v[212:213], off
	v_lshl_add_u64 v[212:213], s[40:41], 0, v[134:135]
	s_add_i32 m0, s46, 0x2000
	s_nop 0
	global_load_lds_dwordx4 v[212:213], off
	v_lshl_add_u64 v[212:213], v[216:217], 0, s[42:43]
	s_mov_b32 m0, s65
	s_nop 0
	global_load_lds_dwordx4 v[212:213], off
	v_lshl_add_u64 v[212:213], v[218:219], 0, s[42:43]
	s_mov_b32 m0, s66
	s_nop 0
	global_load_lds_dwordx4 v[212:213], off
	s_waitcnt vmcnt(8)
	s_waitcnt lgkmcnt(0)
	s_barrier
	s_waitcnt lgkmcnt(0)
	v_mfma_f32_16x16x32_bf16 v[60:63], v[144:147], v[176:179], v[60:63]
	v_mfma_f32_16x16x32_bf16 v[56:59], v[152:155], v[176:179], v[56:59]
	v_mfma_f32_16x16x32_bf16 v[52:55], v[144:147], v[184:187], v[52:55]
	v_mfma_f32_16x16x32_bf16 v[48:51], v[152:155], v[184:187], v[48:51]
	v_mfma_f32_16x16x32_bf16 v[36:39], v[144:147], v[192:195], v[36:39]
	v_mfma_f32_16x16x32_bf16 v[32:35], v[152:155], v[192:195], v[32:35]
	v_mfma_f32_16x16x32_bf16 v[20:23], v[144:147], v[204:207], v[20:23]
	v_mfma_f32_16x16x32_bf16 v[16:19], v[152:155], v[204:207], v[16:19]
	v_mfma_f32_16x16x32_bf16 v[60:63], v[148:151], v[180:183], v[60:63]
	v_mfma_f32_16x16x32_bf16 v[56:59], v[156:159], v[180:183], v[56:59]
	v_mfma_f32_16x16x32_bf16 v[52:55], v[148:151], v[188:191], v[52:55]
	v_mfma_f32_16x16x32_bf16 v[48:51], v[156:159], v[188:191], v[48:51]
	v_mfma_f32_16x16x32_bf16 v[36:39], v[148:151], v[200:203], v[36:39]
	v_mfma_f32_16x16x32_bf16 v[32:35], v[156:159], v[200:203], v[32:35]
	v_mfma_f32_16x16x32_bf16 v[20:23], v[148:151], v[208:211], v[20:23]
	v_mfma_f32_16x16x32_bf16 v[16:19], v[156:159], v[208:211], v[16:19]
	v_mfma_f32_16x16x32_bf16 v[44:47], v[160:163], v[176:179], v[44:47]
	v_mfma_f32_16x16x32_bf16 v[40:43], v[168:171], v[176:179], v[40:43]
	v_mfma_f32_16x16x32_bf16 v[28:31], v[160:163], v[184:187], v[28:31]
	v_mfma_f32_16x16x32_bf16 v[24:27], v[168:171], v[184:187], v[24:27]
	v_mfma_f32_16x16x32_bf16 v[12:15], v[160:163], v[192:195], v[12:15]
	v_mfma_f32_16x16x32_bf16 v[8:11], v[168:171], v[192:195], v[8:11]
	v_mfma_f32_16x16x32_bf16 v[4:7], v[160:163], v[204:207], v[4:7]
	v_mfma_f32_16x16x32_bf16 v[0:3], v[168:171], v[204:207], v[0:3]
	v_mfma_f32_16x16x32_bf16 v[44:47], v[164:167], v[180:183], v[44:47]
	v_mfma_f32_16x16x32_bf16 v[40:43], v[172:175], v[180:183], v[40:43]
	v_mfma_f32_16x16x32_bf16 v[28:31], v[164:167], v[188:191], v[28:31]
	v_mfma_f32_16x16x32_bf16 v[24:27], v[172:175], v[188:191], v[24:27]
	v_mfma_f32_16x16x32_bf16 v[12:15], v[164:167], v[200:203], v[12:15]
	v_mfma_f32_16x16x32_bf16 v[8:11], v[172:175], v[200:203], v[8:11]
	v_mfma_f32_16x16x32_bf16 v[4:7], v[164:167], v[208:211], v[4:7]
	v_mfma_f32_16x16x32_bf16 v[0:3], v[172:175], v[208:211], v[0:3]
	s_barrier
	s_add_i32 s87, s87, 2
	s_add_u32 s85, s85, 0x100
	s_addc_u32 s86, s86, 0
	s_add_u32 s38, s38, 0x100
	s_addc_u32 s39, s39, 0
	s_cmp_gt_u32 s87, 61
	s_cbranch_scc0 .LBB0_270
	s_setprio 0
	s_and_b64 vcc, exec, s[22:23]
	s_cbranch_vccz .LBB0_273
	s_barrier

; #define PG8_STAGE(bufoff, gbase, voff) do { _Pragma("unroll") for (int _i = 0; _i < 2; ++_i) \
;         __builtin_amdgcn_global_load_lds((const unsigned*)((const char*)(gbase) + (voff)[_i]), (PG8_LAS unsigned*)(lds + (bufoff) + ldsw + _i * 8192), 16, 0, 0); } while (0)
; #define PG8_LDA(dst, b, h) do { _Pragma("unroll") for (int m = 0; m < 4; ++m) _Pragma("unroll") for (int k = 0; k < 2; ++k) dst[m][k] = *(const PG8_LAS bf16x8*)(lds + PG8_SA(b, h) + aoff + m * 2048 + k * 1024); } while (0)
; #define PG8_LDB(dst, b, h) do { _Pragma("unroll") for (int n = 0; n < 2; ++n) _Pragma("unroll") for (int k = 0; k < 2; ++k) dst[n][k] = *(const PG8_LAS bf16x8*)(lds + PG8_SB(b, h) + boff + n * 2048 + k * 1024); } while (0)
; #define PG8_WAIT_V(n) asm volatile("s_waitcnt vmcnt(" #n ")" ::: "memory")
; #define PG8_WAIT_L(n) asm volatile("s_waitcnt lgkmcnt(" #n ")" ::: "memory")
; #define PG8_BAR __builtin_amdgcn_s_barrier()
; #define PG8_SCHED __builtin_amdgcn_sched_barrier(0)
; template <class Epi, class Sched, bool ALIGN_EPI = false, bool SP2 = false, bool I8 = false>
; __device__ __forceinline__ void gemm_phase(PG8_LAS unsigned char* lds, const Gemm g, const Sched& S, const Epi& E, const int tid) {
;     ...
;     for (;;) {
;         const bool has_next = S.next(ui + 1, nxt);
;         const char* nA = has_next ? (const char*)g.A + (size_t)nxt.pm * tstepA : cA; const char* nB = has_next ? (const char*)g.Bt + (size_t)nxt.pn * tstepB : cB;
;         for (int t = 0; t < nt; t += 2) {
;             const bool last = (t == nt - 2);
;             const char* a1 = cA + (size_t)(t + 1) * kstep;
;             const char* a2 = last ? nA : cA + (size_t)(t + 2) * kstep; const char* b2 = last ? nB : cB + (size_t)(t + 2) * kstep;
;             const char* a3 = a2 + kstep; const char* b3 = b2 + kstep;
;             if (last && has_next) S.a_ready(nxt);
;             if constexpr (SP2) {
;             PG8_LDB(B0, 0, 0); PG8_LDB(B1, 0, 1); PG8_SCHED; PG8_LDA(At, 0, 0); PG8_STAGE(PG8_SA(1, 1), a1 + hstepA, voffA);
;             PG8_WAIT_V(8); PG8_WAIT_L(0); PG8_BAR; PG8_MMA(0, 0, At, B0); PG8_MMA(0, 1, At, B1); PG8_BAR; PG8_SCHED;
;     ...
;         for (int a = 0; a < 2; ++a)
; #pragma unroll
;             for (int b = 0; b < 2; ++b)
; #pragma unroll
;                 for (int m = 0; m < 4; ++m)
; #pragma unroll
;                     for (int n = 0; n < 2; ++n) acc[a][b][m][n] = AccT<I8>::zero();
.LBB0_334:
	s_ashr_i32 s31, s30, 31
	s_lshl_b64 s[34:35], s[30:31], 20
	s_add_u32 s34, s73, s34
	s_addc_u32 s35, s74, s35
	s_and_b64 s[38:39], s[36:37], exec
	s_cselect_b32 s5, s35, s55
	s_cselect_b32 s31, s34, s54
	s_ashr_i32 s13, s12, 31
	s_lshl_b64 s[38:39], s[12:13], 20
	s_add_u32 s38, s9, s38
	s_addc_u32 s39, s66, s39
	s_and_b64 s[56:57], s[36:37], exec
	s_cselect_b32 s13, s39, s47
	s_cselect_b32 s41, s38, s46
	s_add_u32 s49, s46, 0x100
	s_addc_u32 s60, s47, 0
	s_add_u32 s46, s54, 0x80080
	v_mov_b32_e32 v0, 0
	s_addc_u32 s47, s55, 0
	s_mov_b32 s65, -2
	v_mov_b32_e32 v1, v0
	v_mov_b32_e32 v2, v0
	v_mov_b32_e32 v3, v0
	v_mov_b32_e32 v4, v0
	v_mov_b32_e32 v5, v0
	v_mov_b32_e32 v6, v0
	v_mov_b32_e32 v7, v0
	v_mov_b32_e32 v16, v0
	v_mov_b32_e32 v17, v0
	v_mov_b32_e32 v18, v0
	v_mov_b32_e32 v19, v0
	v_mov_b32_e32 v20, v0
	v_mov_b32_e32 v21, v0
	v_mov_b32_e32 v22, v0
	v_mov_b32_e32 v23, v0
	v_mov_b32_e32 v32, v0
	v_mov_b32_e32 v33, v0
	v_mov_b32_e32 v34, v0
	v_mov_b32_e32 v35, v0
	v_mov_b32_e32 v36, v0
	v_mov_b32_e32 v37, v0
	v_mov_b32_e32 v38, v0
	v_mov_b32_e32 v39, v0
	v_mov_b32_e32 v56, v0
	v_mov_b32_e32 v57, v0
	v_mov_b32_e32 v58, v0
	v_mov_b32_e32 v59, v0
	v_mov_b32_e32 v60, v0
	v_mov_b32_e32 v61, v0
	v_mov_b32_e32 v62, v0
	v_mov_b32_e32 v63, v0
	v_mov_b32_e32 v8, v0
	v_mov_b32_e32 v9, v0
	v_mov_b32_e32 v10, v0
	v_mov_b32_e32 v11, v0
	v_mov_b32_e32 v12, v0
	v_mov_b32_e32 v13, v0
	v_mov_b32_e32 v14, v0
	v_mov_b32_e32 v15, v0
	v_mov_b32_e32 v24, v0
	v_mov_b32_e32 v25, v0
	v_mov_b32_e32 v26, v0
	v_mov_b32_e32 v27, v0
	v_mov_b32_e32 v28, v0
	v_mov_b32_e32 v29, v0
	v_mov_b32_e32 v30, v0
	v_mov_b32_e32 v31, v0
	v_mov_b32_e32 v40, v0
	v_mov_b32_e32 v41, v0
	v_mov_b32_e32 v42, v0
	v_mov_b32_e32 v43, v0
	v_mov_b32_e32 v44, v0
	v_mov_b32_e32 v45, v0
	v_mov_b32_e32 v46, v0
	v_mov_b32_e32 v47, v0
	v_mov_b32_e32 v72, v0
	v_mov_b32_e32 v73, v0
	v_mov_b32_e32 v74, v0
	v_mov_b32_e32 v75, v0
	v_mov_b32_e32 v76, v0
	v_mov_b32_e32 v77, v0
	v_mov_b32_e32 v78, v0
	v_mov_b32_e32 v79, v0
	v_mov_b32_e32 v80, v0
	v_mov_b32_e32 v81, v0
	v_mov_b32_e32 v82, v0
	v_mov_b32_e32 v83, v0
	v_mov_b32_e32 v84, v0
	v_mov_b32_e32 v85, v0
	v_mov_b32_e32 v86, v0
	v_mov_b32_e32 v87, v0
	v_mov_b32_e32 v98, v0
	v_mov_b32_e32 v99, v0
	v_mov_b32_e32 v100, v0
	v_mov_b32_e32 v101, v0
	v_mov_b32_e32 v102, v0
	v_mov_b32_e32 v103, v0
	v_mov_b32_e32 v104, v0
	v_mov_b32_e32 v105, v0
	v_mov_b32_e32 v114, v0
	v_mov_b32_e32 v115, v0
	v_mov_b32_e32 v116, v0
	v_mov_b32_e32 v117, v0
	v_mov_b32_e32 v118, v0
	v_mov_b32_e32 v119, v0
	v_mov_b32_e32 v120, v0
	v_mov_b32_e32 v121, v0
	v_mov_b32_e32 v130, v0
	v_mov_b32_e32 v131, v0
	v_mov_b32_e32 v132, v0
	v_mov_b32_e32 v133, v0
	v_mov_b32_e32 v134, v0
	v_mov_b32_e32 v135, v0
	v_mov_b32_e32 v136, v0
	v_mov_b32_e32 v137, v0
	v_mov_b32_e32 v88, v0
	v_mov_b32_e32 v89, v0
	v_mov_b32_e32 v90, v0
	v_mov_b32_e32 v91, v0
	v_mov_b32_e32 v92, v0
	v_mov_b32_e32 v93, v0
	v_mov_b32_e32 v94, v0
	v_mov_b32_e32 v95, v0
	v_mov_b32_e32 v106, v0
	v_mov_b32_e32 v107, v0
	v_mov_b32_e32 v108, v0
	v_mov_b32_e32 v109, v0
	v_mov_b32_e32 v110, v0
	v_mov_b32_e32 v111, v0
	v_mov_b32_e32 v112, v0
	v_mov_b32_e32 v113, v0
	v_mov_b32_e32 v122, v0
	v_mov_b32_e32 v123, v0
	v_mov_b32_e32 v124, v0
	v_mov_b32_e32 v125, v0
	v_mov_b32_e32 v126, v0
	v_mov_b32_e32 v127, v0
	v_mov_b32_e32 v128, v0
	v_mov_b32_e32 v129, v0
	v_mov_b32_e32 v138, v0
	v_mov_b32_e32 v139, v0
	v_mov_b32_e32 v140, v0
	v_mov_b32_e32 v141, v0
	v_mov_b32_e32 v142, v0
	v_mov_b32_e32 v143, v0
	v_mov_b32_e32 v144, v0
	v_mov_b32_e32 v145, v0
	s_cmp_lg_u64 s[26:27], 0
	s_cbranch_scc1 .Lgprio_335
	s_setprio 1
.Lgprio_335:
.LBB0_335:
	s_add_u32 s54, s46, 0xfff80080
	s_addc_u32 s55, s47, -1
	s_add_i32 s70, 0, 0x10000
	s_cmp_eq_u32 s65, 28
	s_cselect_b32 s57, s5, s55
	s_cselect_b32 s56, s31, s54
	s_cselect_b32 s55, s13, s60
	s_cselect_b32 s54, s41, s49
	s_add_i32 s87, 0, 0x14000
	v_add_u32_e32 v68, s70, v187
	v_add_u32_e32 v168, s87, v187
	ds_read_b128 v[48:51], v68
	ds_read_b128 v[52:55], v68 offset:1024
	ds_read_b128 v[64:67], v68 offset:2048
	ds_read_b128 v[68:71], v68 offset:3072
	ds_read_b128 v[156:159], v168
	ds_read_b128 v[160:163], v168 offset:1024
	ds_read_b128 v[164:167], v168 offset:2048
	ds_read_b128 v[168:171], v168 offset:3072
	v_lshl_add_u64 v[184:185], s[46:47], 0, v[154:155]
	s_add_i32 m0, s80, 0xc000
	ds_read_b128 v[172:175], v189
	ds_read_b128 v[176:179], v189 offset:1024
	ds_read_b128 v[180:183], v189 offset:2048
	ds_read_b128 v[190:193], v189 offset:3072
	ds_read_b128 v[200:203], v189 offset:4096
	ds_read_b128 v[204:207], v189 offset:5120
	ds_read_b128 v[208:211], v189 offset:6144
	ds_read_b128 v[212:215], v189 offset:7168
	global_load_lds_dwordx4 v[184:185], off
	v_lshl_add_u64 v[184:185], s[46:47], 0, v[152:153]
	s_add_i32 m0, s80, 0xe000
	s_nop 0
	global_load_lds_dwordx4 v[184:185], off
	s_waitcnt vmcnt(8)
	s_waitcnt lgkmcnt(0)
	s_barrier
; #define PG8_STAGE(bufoff, gbase, voff) do { _Pragma("unroll") for (int _i = 0; _i < 2; ++_i) \
;         __builtin_amdgcn_global_load_lds((const unsigned*)((const char*)(gbase) + (voff)[_i]), (PG8_LAS unsigned*)(lds + (bufoff) + ldsw + _i * 8192), 16, 0, 0); } while (0)
; #define PG8_LDA(dst, b, h) do { _Pragma("unroll") for (int m = 0; m < 4; ++m) _Pragma("unroll") for (int k = 0; k < 2; ++k) dst[m][k] = *(const PG8_LAS bf16x8*)(lds + PG8_SA(b, h) + aoff + m * 2048 + k * 1024); } while (0)
; #define PG8_LDB(dst, b, h) do { _Pragma("unroll") for (int n = 0; n < 2; ++n) _Pragma("unroll") for (int k = 0; k < 2; ++k) dst[n][k] = *(const PG8_LAS bf16x8*)(lds + PG8_SB(b, h) + boff + n * 2048 + k * 1024); } while (0)
; #define PG8_MMA(ai, bj, At, Bt) do { __builtin_amdgcn_s_setprio(1); _Pragma("unroll") for (int m = 0; m < 4; ++m) _Pragma("unroll") for (int n = 0; n < 2; ++n) _Pragma("unroll") for (int k = 0; k < 2; ++k) \
;         mma1<I8>(acc[ai][bj][m][n], Bt[n][k], At[m][k]); __builtin_amdgcn_s_setprio(0); } while (0)
; #define PG8_WAIT_V(n) asm volatile("s_waitcnt vmcnt(" #n ")" ::: "memory")
; #define PG8_WAIT_L(n) asm volatile("s_waitcnt lgkmcnt(" #n ")" ::: "memory")
; #define PG8_BAR __builtin_amdgcn_s_barrier()
; #define PG8_SCHED __builtin_amdgcn_sched_barrier(0)
; template <class Epi, class Sched, bool ALIGN_EPI = false, bool SP2 = false, bool I8 = false>
; __device__ __forceinline__ void gemm_phase(PG8_LAS unsigned char* lds, const Gemm g, const Sched& S, const Epi& E, const int tid) {
;     ...
;             PG8_LDB(B0, 0, 0); PG8_LDB(B1, 0, 1); PG8_SCHED; PG8_LDA(At, 0, 0); PG8_STAGE(PG8_SA(1, 1), a1 + hstepA, voffA);
;             PG8_WAIT_V(8); PG8_WAIT_L(0); PG8_BAR; PG8_MMA(0, 0, At, B0); PG8_MMA(0, 1, At, B1); PG8_BAR; PG8_SCHED;
;             PG8_LDA(At, 0, 1); PG8_STAGE(PG8_SB(0, 0), b2, voffB); PG8_STAGE(PG8_SB(0, 1), b2 + hstepB, voffB); PG8_STAGE(PG8_SA(0, 0), a2, voffA);
;             PG8_WAIT_V(8); PG8_WAIT_L(0); PG8_BAR; PG8_MMA(1, 0, At, B0); PG8_MMA(1, 1, At, B1); PG8_BAR; PG8_SCHED;
	s_waitcnt lgkmcnt(0)
	v_mfma_i32_16x16x64_i8 v[142:145], v[48:51], v[172:175], v[142:145]
	v_mfma_i32_16x16x64_i8 v[138:141], v[64:67], v[172:175], v[138:141]
	v_mfma_i32_16x16x64_i8 v[126:129], v[48:51], v[180:183], v[126:129]
	v_mfma_i32_16x16x64_i8 v[122:125], v[64:67], v[180:183], v[122:125]
	v_mfma_i32_16x16x64_i8 v[110:113], v[48:51], v[200:203], v[110:113]
	v_mfma_i32_16x16x64_i8 v[106:109], v[64:67], v[200:203], v[106:109]
	v_mfma_i32_16x16x64_i8 v[92:95], v[48:51], v[208:211], v[92:95]
	v_mfma_i32_16x16x64_i8 v[88:91], v[64:67], v[208:211], v[88:91]
	v_mfma_i32_16x16x64_i8 v[142:145], v[52:55], v[176:179], v[142:145]
	v_mfma_i32_16x16x64_i8 v[138:141], v[68:71], v[176:179], v[138:141]
	v_mfma_i32_16x16x64_i8 v[126:129], v[52:55], v[190:193], v[126:129]
	v_mfma_i32_16x16x64_i8 v[122:125], v[68:71], v[190:193], v[122:125]
	v_mfma_i32_16x16x64_i8 v[110:113], v[52:55], v[204:207], v[110:113]
	v_mfma_i32_16x16x64_i8 v[106:109], v[68:71], v[204:207], v[106:109]
	v_mfma_i32_16x16x64_i8 v[92:95], v[52:55], v[212:215], v[92:95]
	v_mfma_i32_16x16x64_i8 v[88:91], v[68:71], v[212:215], v[88:91]
	v_mfma_i32_16x16x64_i8 v[134:137], v[156:159], v[172:175], v[134:137]
	v_mfma_i32_16x16x64_i8 v[130:133], v[164:167], v[172:175], v[130:133]
	v_mfma_i32_16x16x64_i8 v[118:121], v[156:159], v[180:183], v[118:121]
	v_mfma_i32_16x16x64_i8 v[114:117], v[164:167], v[180:183], v[114:117]
	v_mfma_i32_16x16x64_i8 v[102:105], v[156:159], v[200:203], v[102:105]
	v_mfma_i32_16x16x64_i8 v[98:101], v[164:167], v[200:203], v[98:101]
	v_mfma_i32_16x16x64_i8 v[84:87], v[156:159], v[208:211], v[84:87]
	v_mfma_i32_16x16x64_i8 v[80:83], v[164:167], v[208:211], v[80:83]
	v_mfma_i32_16x16x64_i8 v[134:137], v[160:163], v[176:179], v[134:137]
	v_mfma_i32_16x16x64_i8 v[130:133], v[168:171], v[176:179], v[130:133]
	v_mfma_i32_16x16x64_i8 v[118:121], v[160:163], v[190:193], v[118:121]
	v_mfma_i32_16x16x64_i8 v[114:117], v[168:171], v[190:193], v[114:117]
	v_mfma_i32_16x16x64_i8 v[102:105], v[160:163], v[204:207], v[102:105]
	v_mfma_i32_16x16x64_i8 v[98:101], v[168:171], v[204:207], v[98:101]
	v_mfma_i32_16x16x64_i8 v[84:87], v[160:163], v[212:215], v[84:87]
	v_mfma_i32_16x16x64_i8 v[80:83], v[168:171], v[212:215], v[80:83]
	s_barrier
	s_add_i32 s70, s70, s75
	v_lshl_add_u64 v[184:185], s[54:55], 0, v[96:97]
	s_mov_b32 m0, s70
	ds_read_b128 v[172:175], v189 offset:16384
	ds_read_b128 v[176:179], v189 offset:17408
	ds_read_b128 v[180:183], v189 offset:18432
	ds_read_b128 v[190:193], v189 offset:19456
	ds_read_b128 v[200:203], v189 offset:20480
	ds_read_b128 v[204:207], v189 offset:21504
	ds_read_b128 v[208:211], v189 offset:22528
	ds_read_b128 v[212:215], v189 offset:23552
	global_load_lds_dwordx4 v[184:185], off
	s_add_i32 m0, s70, 0x2000
	s_add_u32 s76, s54, 0x80000
	v_lshl_add_u64 v[194:195], s[54:55], 0, v[150:151]
	s_addc_u32 s77, s55, 0
	s_add_i32 s70, s87, s75
	global_load_lds_dwordx4 v[194:195], off
	v_lshl_add_u64 v[216:217], s[76:77], 0, v[96:97]
	s_mov_b32 m0, s70
	v_lshl_add_u64 v[218:219], s[56:57], 0, v[148:149]
	global_load_lds_dwordx4 v[216:217], off
	v_lshl_add_u64 v[216:217], s[76:77], 0, v[150:151]
	s_add_i32 m0, s70, 0x2000
	s_nop 0
	global_load_lds_dwordx4 v[216:217], off
	v_lshl_add_u64 v[216:217], s[56:57], 0, v[146:147]
	s_mov_b32 m0, s80
	s_nop 0
	global_load_lds_dwordx4 v[216:217], off
	s_mov_b32 m0, s85
	s_nop 0
	global_load_lds_dwordx4 v[218:219], off
	s_waitcnt vmcnt(8)
	s_waitcnt lgkmcnt(0)
	s_barrier
	s_waitcnt lgkmcnt(0)
	v_mfma_i32_16x16x64_i8 v[76:79], v[48:51], v[172:175], v[76:79]
	v_mfma_i32_16x16x64_i8 v[72:75], v[64:67], v[172:175], v[72:75]
	v_mfma_i32_16x16x64_i8 v[44:47], v[48:51], v[180:183], v[44:47]
	v_mfma_i32_16x16x64_i8 v[40:43], v[64:67], v[180:183], v[40:43]
	v_mfma_i32_16x16x64_i8 v[28:31], v[48:51], v[200:203], v[28:31]
	v_mfma_i32_16x16x64_i8 v[24:27], v[64:67], v[200:203], v[24:27]
	v_mfma_i32_16x16x64_i8 v[12:15], v[48:51], v[208:211], v[12:15]
	v_mfma_i32_16x16x64_i8 v[8:11], v[64:67], v[208:211], v[8:11]
	v_mfma_i32_16x16x64_i8 v[76:79], v[52:55], v[176:179], v[76:79]
	v_mfma_i32_16x16x64_i8 v[72:75], v[68:71], v[176:179], v[72:75]
	v_mfma_i32_16x16x64_i8 v[44:47], v[52:55], v[190:193], v[44:47]
	v_mfma_i32_16x16x64_i8 v[40:43], v[68:71], v[190:193], v[40:43]
	v_mfma_i32_16x16x64_i8 v[28:31], v[52:55], v[204:207], v[28:31]
	v_mfma_i32_16x16x64_i8 v[24:27], v[68:71], v[204:207], v[24:27]
	v_mfma_i32_16x16x64_i8 v[12:15], v[52:55], v[212:215], v[12:15]
	v_mfma_i32_16x16x64_i8 v[8:11], v[68:71], v[212:215], v[8:11]
	v_mfma_i32_16x16x64_i8 v[36:39], v[156:159], v[180:183], v[36:39]
	v_mfma_i32_16x16x64_i8 v[32:35], v[164:167], v[180:183], v[32:35]
	v_mfma_i32_16x16x64_i8 v[20:23], v[156:159], v[200:203], v[20:23]
	v_mfma_i32_16x16x64_i8 v[16:19], v[164:167], v[200:203], v[16:19]
	v_mfma_i32_16x16x64_i8 v[4:7], v[156:159], v[208:211], v[4:7]
	v_mfma_i32_16x16x64_i8 v[0:3], v[164:167], v[208:211], v[0:3]
	v_mfma_i32_16x16x64_i8 v[48:51], v[156:159], v[172:175], v[60:63]
	v_mfma_i32_16x16x64_i8 v[52:55], v[164:167], v[172:175], v[56:59]
	v_mfma_i32_16x16x64_i8 v[36:39], v[160:163], v[190:193], v[36:39]
	v_mfma_i32_16x16x64_i8 v[32:35], v[168:171], v[190:193], v[32:35]
	v_mfma_i32_16x16x64_i8 v[20:23], v[160:163], v[204:207], v[20:23]
	v_mfma_i32_16x16x64_i8 v[16:19], v[168:171], v[204:207], v[16:19]
	v_mfma_i32_16x16x64_i8 v[4:7], v[160:163], v[212:215], v[4:7]
	v_mfma_i32_16x16x64_i8 v[0:3], v[168:171], v[212:215], v[0:3]
	v_mfma_i32_16x16x64_i8 v[48:51], v[160:163], v[176:179], v[48:51]
	v_mfma_i32_16x16x64_i8 v[52:55], v[168:171], v[176:179], v[52:55]
	s_barrier
; #define PG8_STAGE(bufoff, gbase, voff) do { _Pragma("unroll") for (int _i = 0; _i < 2; ++_i) \
;         __builtin_amdgcn_global_load_lds((const unsigned*)((const char*)(gbase) + (voff)[_i]), (PG8_LAS unsigned*)(lds + (bufoff) + ldsw + _i * 8192), 16, 0, 0); } while (0)
; #define PG8_LDA(dst, b, h) do { _Pragma("unroll") for (int m = 0; m < 4; ++m) _Pragma("unroll") for (int k = 0; k < 2; ++k) dst[m][k] = *(const PG8_LAS bf16x8*)(lds + PG8_SA(b, h) + aoff + m * 2048 + k * 1024); } while (0)
; #define PG8_LDB(dst, b, h) do { _Pragma("unroll") for (int n = 0; n < 2; ++n) _Pragma("unroll") for (int k = 0; k < 2; ++k) dst[n][k] = *(const PG8_LAS bf16x8*)(lds + PG8_SB(b, h) + boff + n * 2048 + k * 1024); } while (0)
; #define PG8_MMA(ai, bj, At, Bt) do { __builtin_amdgcn_s_setprio(1); _Pragma("unroll") for (int m = 0; m < 4; ++m) _Pragma("unroll") for (int n = 0; n < 2; ++n) _Pragma("unroll") for (int k = 0; k < 2; ++k) \
;         mma1<I8>(acc[ai][bj][m][n], Bt[n][k], At[m][k]); __builtin_amdgcn_s_setprio(0); } while (0)
; #define PG8_WAIT_V(n) asm volatile("s_waitcnt vmcnt(" #n ")" ::: "memory")
; #define PG8_WAIT_L(n) asm volatile("s_waitcnt lgkmcnt(" #n ")" ::: "memory")
; #define PG8_BAR __builtin_amdgcn_s_barrier()
; #define PG8_SCHED __builtin_amdgcn_sched_barrier(0)
; template <class Epi, class Sched, bool ALIGN_EPI = false, bool SP2 = false, bool I8 = false>
; __device__ __forceinline__ void gemm_phase(PG8_LAS unsigned char* lds, const Gemm g, const Sched& S, const Epi& E, const int tid) {
;     ...
;             PG8_LDB(B0, 1, 0); PG8_LDB(B1, 1, 1); PG8_SCHED; PG8_LDA(At, 1, 0); PG8_STAGE(PG8_SA(0, 1), a2 + hstepA, voffA);
;             PG8_WAIT_V(8); PG8_WAIT_L(0); PG8_BAR; PG8_MMA(0, 0, At, B0); PG8_MMA(0, 1, At, B1); PG8_BAR; PG8_SCHED;
;             PG8_LDA(At, 1, 1); PG8_STAGE(PG8_SB(1, 0), b3, voffB); PG8_STAGE(PG8_SB(1, 1), b3 + hstepB, voffB); PG8_STAGE(PG8_SA(1, 0), a3, voffA);
;             PG8_WAIT_V(8); PG8_WAIT_L(0); PG8_BAR; PG8_MMA(1, 0, At, B0); PG8_MMA(1, 1, At, B1); PG8_BAR; PG8_SCHED;
;     ...
;         if constexpr (ALIGN_EPI) { if (wr == 0) PG8_BAR; }
	s_add_i32 s70, 0, 0x18000
	s_add_i32 s76, 0, 0x1c000
	v_add_u32_e32 v68, s70, v187
	v_add_u32_e32 v168, s76, v187
	ds_read_b128 v[56:59], v68
	ds_read_b128 v[60:63], v68 offset:1024
	ds_read_b128 v[64:67], v68 offset:2048
	ds_read_b128 v[68:71], v68 offset:3072
	ds_read_b128 v[156:159], v168
	ds_read_b128 v[160:163], v168 offset:1024
	ds_read_b128 v[164:167], v168 offset:2048
	ds_read_b128 v[168:171], v168 offset:3072
	s_add_u32 s56, s56, 0x80000
	s_addc_u32 s57, s57, 0
	s_mov_b32 m0, s86
	v_lshl_add_u64 v[220:221], s[56:57], 0, v[146:147]
	ds_read_b128 v[172:175], v189 offset:32768
	ds_read_b128 v[176:179], v189 offset:33792
	ds_read_b128 v[180:183], v189 offset:34816
	ds_read_b128 v[190:193], v189 offset:35840
	ds_read_b128 v[200:203], v189 offset:36864
	ds_read_b128 v[204:207], v189 offset:37888
	ds_read_b128 v[208:211], v189 offset:38912
	ds_read_b128 v[212:215], v189 offset:39936
	global_load_lds_dwordx4 v[220:221], off
	v_lshl_add_u64 v[220:221], s[56:57], 0, v[148:149]
	s_mov_b32 m0, s88
	s_nop 0
	global_load_lds_dwordx4 v[220:221], off
	s_waitcnt vmcnt(8)
	s_waitcnt lgkmcnt(0)
	s_barrier
	s_waitcnt lgkmcnt(0)
	v_mfma_i32_16x16x64_i8 v[142:145], v[56:59], v[172:175], v[142:145]
	v_mfma_i32_16x16x64_i8 v[138:141], v[64:67], v[172:175], v[138:141]
	v_mfma_i32_16x16x64_i8 v[126:129], v[56:59], v[180:183], v[126:129]
	v_mfma_i32_16x16x64_i8 v[122:125], v[64:67], v[180:183], v[122:125]
	v_mfma_i32_16x16x64_i8 v[110:113], v[56:59], v[200:203], v[110:113]
	v_mfma_i32_16x16x64_i8 v[106:109], v[64:67], v[200:203], v[106:109]
	v_mfma_i32_16x16x64_i8 v[92:95], v[56:59], v[208:211], v[92:95]
	v_mfma_i32_16x16x64_i8 v[88:91], v[64:67], v[208:211], v[88:91]
	v_mfma_i32_16x16x64_i8 v[142:145], v[60:63], v[176:179], v[142:145]
	v_mfma_i32_16x16x64_i8 v[138:141], v[68:71], v[176:179], v[138:141]
	v_mfma_i32_16x16x64_i8 v[126:129], v[60:63], v[190:193], v[126:129]
	v_mfma_i32_16x16x64_i8 v[122:125], v[68:71], v[190:193], v[122:125]
	v_mfma_i32_16x16x64_i8 v[110:113], v[60:63], v[204:207], v[110:113]
	v_mfma_i32_16x16x64_i8 v[106:109], v[68:71], v[204:207], v[106:109]
	v_mfma_i32_16x16x64_i8 v[92:95], v[60:63], v[212:215], v[92:95]
	v_mfma_i32_16x16x64_i8 v[88:91], v[68:71], v[212:215], v[88:91]
	v_mfma_i32_16x16x64_i8 v[134:137], v[156:159], v[172:175], v[134:137]
	v_mfma_i32_16x16x64_i8 v[130:133], v[164:167], v[172:175], v[130:133]
	v_mfma_i32_16x16x64_i8 v[118:121], v[156:159], v[180:183], v[118:121]
	v_mfma_i32_16x16x64_i8 v[114:117], v[164:167], v[180:183], v[114:117]
	v_mfma_i32_16x16x64_i8 v[102:105], v[156:159], v[200:203], v[102:105]
	v_mfma_i32_16x16x64_i8 v[98:101], v[164:167], v[200:203], v[98:101]
	v_mfma_i32_16x16x64_i8 v[84:87], v[156:159], v[208:211], v[84:87]
	v_mfma_i32_16x16x64_i8 v[80:83], v[164:167], v[208:211], v[80:83]
	v_mfma_i32_16x16x64_i8 v[134:137], v[160:163], v[176:179], v[134:137]
	v_mfma_i32_16x16x64_i8 v[130:133], v[168:171], v[176:179], v[130:133]
	v_mfma_i32_16x16x64_i8 v[118:121], v[160:163], v[190:193], v[118:121]
	v_mfma_i32_16x16x64_i8 v[114:117], v[168:171], v[190:193], v[114:117]
	v_mfma_i32_16x16x64_i8 v[102:105], v[160:163], v[204:207], v[102:105]
	v_mfma_i32_16x16x64_i8 v[98:101], v[168:171], v[204:207], v[98:101]
	v_mfma_i32_16x16x64_i8 v[84:87], v[160:163], v[212:215], v[84:87]
	v_mfma_i32_16x16x64_i8 v[80:83], v[168:171], v[212:215], v[80:83]
	s_barrier
	s_add_i32 s56, s70, s75
	v_lshl_add_u64 v[184:185], v[184:185], 0, s[42:43]
	s_mov_b32 m0, s56
	ds_read_b128 v[172:175], v189 offset:49152
	ds_read_b128 v[176:179], v189 offset:50176
	ds_read_b128 v[180:183], v189 offset:51200
	ds_read_b128 v[190:193], v189 offset:52224
	ds_read_b128 v[200:203], v189 offset:53248
	ds_read_b128 v[204:207], v189 offset:54272
	ds_read_b128 v[208:211], v189 offset:55296
	ds_read_b128 v[212:215], v189 offset:56320
	global_load_lds_dwordx4 v[184:185], off
	s_add_i32 m0, s56, 0x2000
	s_add_u32 s54, s54, 0x80080
	v_lshl_add_u64 v[184:185], v[194:195], 0, s[42:43]
	s_addc_u32 s55, s55, 0
	s_add_i32 s56, s76, s75
	global_load_lds_dwordx4 v[184:185], off
	v_lshl_add_u64 v[184:185], s[54:55], 0, v[96:97]
	s_mov_b32 m0, s56
	s_nop 0
	global_load_lds_dwordx4 v[184:185], off
	v_lshl_add_u64 v[184:185], s[54:55], 0, v[150:151]
	s_add_i32 m0, s56, 0x2000
	s_nop 0
	global_load_lds_dwordx4 v[184:185], off
	v_lshl_add_u64 v[184:185], v[216:217], 0, s[42:43]
	s_mov_b32 m0, s89
	s_nop 0
	global_load_lds_dwordx4 v[184:185], off
	v_lshl_add_u64 v[184:185], v[218:219], 0, s[42:43]
	s_mov_b32 m0, s90
	s_nop 0
	global_load_lds_dwordx4 v[184:185], off
	s_waitcnt vmcnt(8)
	s_waitcnt lgkmcnt(0)
	s_barrier
	s_waitcnt lgkmcnt(0)
	v_mfma_i32_16x16x64_i8 v[76:79], v[56:59], v[172:175], v[76:79]
	v_mfma_i32_16x16x64_i8 v[72:75], v[64:67], v[172:175], v[72:75]
	v_mfma_i32_16x16x64_i8 v[44:47], v[56:59], v[180:183], v[44:47]
	v_mfma_i32_16x16x64_i8 v[40:43], v[64:67], v[180:183], v[40:43]
	v_mfma_i32_16x16x64_i8 v[28:31], v[56:59], v[200:203], v[28:31]
	v_mfma_i32_16x16x64_i8 v[24:27], v[64:67], v[200:203], v[24:27]
	v_mfma_i32_16x16x64_i8 v[12:15], v[56:59], v[208:211], v[12:15]
	v_mfma_i32_16x16x64_i8 v[8:11], v[64:67], v[208:211], v[8:11]
	v_mfma_i32_16x16x64_i8 v[76:79], v[60:63], v[176:179], v[76:79]
	v_mfma_i32_16x16x64_i8 v[72:75], v[68:71], v[176:179], v[72:75]
	v_mfma_i32_16x16x64_i8 v[44:47], v[60:63], v[190:193], v[44:47]
	v_mfma_i32_16x16x64_i8 v[40:43], v[68:71], v[190:193], v[40:43]
	v_mfma_i32_16x16x64_i8 v[28:31], v[60:63], v[204:207], v[28:31]
	v_mfma_i32_16x16x64_i8 v[24:27], v[68:71], v[204:207], v[24:27]
	v_mfma_i32_16x16x64_i8 v[12:15], v[60:63], v[212:215], v[12:15]
	v_mfma_i32_16x16x64_i8 v[8:11], v[68:71], v[212:215], v[8:11]
	v_mfma_i32_16x16x64_i8 v[48:51], v[156:159], v[172:175], v[48:51]
	v_mfma_i32_16x16x64_i8 v[60:63], v[160:163], v[176:179], v[48:51]
	v_mfma_i32_16x16x64_i8 v[48:51], v[164:167], v[172:175], v[52:55]
	v_mfma_i32_16x16x64_i8 v[36:39], v[156:159], v[180:183], v[36:39]
	v_mfma_i32_16x16x64_i8 v[32:35], v[164:167], v[180:183], v[32:35]
	v_mfma_i32_16x16x64_i8 v[20:23], v[156:159], v[200:203], v[20:23]
	v_mfma_i32_16x16x64_i8 v[16:19], v[164:167], v[200:203], v[16:19]
	v_mfma_i32_16x16x64_i8 v[4:7], v[156:159], v[208:211], v[4:7]
	v_mfma_i32_16x16x64_i8 v[0:3], v[164:167], v[208:211], v[0:3]
	v_mfma_i32_16x16x64_i8 v[56:59], v[168:171], v[176:179], v[48:51]
	v_mfma_i32_16x16x64_i8 v[36:39], v[160:163], v[190:193], v[36:39]
	v_mfma_i32_16x16x64_i8 v[32:35], v[168:171], v[190:193], v[32:35]
	v_mfma_i32_16x16x64_i8 v[20:23], v[160:163], v[204:207], v[20:23]
	v_mfma_i32_16x16x64_i8 v[16:19], v[168:171], v[204:207], v[16:19]
	v_mfma_i32_16x16x64_i8 v[4:7], v[160:163], v[212:215], v[4:7]
	v_mfma_i32_16x16x64_i8 v[0:3], v[168:171], v[212:215], v[0:3]
	s_barrier
	s_add_i32 s65, s65, 2
	s_add_u32 s49, s49, 0x100
	s_addc_u32 s60, s60, 0
	s_add_u32 s46, s46, 0x100
	s_addc_u32 s47, s47, 0
	s_cmp_gt_u32 s65, 29
	s_cbranch_scc0 .LBB0_335
	s_setprio 0
	s_and_b64 vcc, exec, s[26:27]
	s_cbranch_vccz .LBB0_338
	s_barrier

; #define PG8_STAGE(bufoff, gbase, voff) do { _Pragma("unroll") for (int _i = 0; _i < 2; ++_i) \
;         __builtin_amdgcn_global_load_lds((const unsigned*)((const char*)(gbase) + (voff)[_i]), (PG8_LAS unsigned*)(lds + (bufoff) + ldsw + _i * 8192), 16, 0, 0); } while (0)
; #define PG8_LDA(dst, b, h) do { _Pragma("unroll") for (int m = 0; m < 4; ++m) _Pragma("unroll") for (int k = 0; k < 2; ++k) dst[m][k] = *(const PG8_LAS bf16x8*)(lds + PG8_SA(b, h) + aoff + m * 2048 + k * 1024); } while (0)
; #define PG8_LDB(dst, b, h) do { _Pragma("unroll") for (int n = 0; n < 2; ++n) _Pragma("unroll") for (int k = 0; k < 2; ++k) dst[n][k] = *(const PG8_LAS bf16x8*)(lds + PG8_SB(b, h) + boff + n * 2048 + k * 1024); } while (0)
; #define PG8_WAIT_V(n) asm volatile("s_waitcnt vmcnt(" #n ")" ::: "memory")
; template <class Epi, class Sched, bool ALIGN_EPI = false, bool SP2 = false, bool I8 = false>
; __device__ __forceinline__ void gemm_phase(PG8_LAS unsigned char* lds, const Gemm g, const Sched& S, const Epi& E, const int tid) {
;     ...
;         const bool has_next = S.next(ui + 1, nxt);
;         const char* nA = has_next ? (const char*)g.A + (size_t)nxt.pm * tstepA : cA; const char* nB = has_next ? (const char*)g.Bt + (size_t)nxt.pn * tstepB : cB;
;         for (int t = 0; t < nt; t += 2) {
;             const bool last = (t == nt - 2);
;             const char* a1 = cA + (size_t)(t + 1) * kstep;
;             const char* a2 = last ? nA : cA + (size_t)(t + 2) * kstep; const char* b2 = last ? nB : cB + (size_t)(t + 2) * kstep;
;             const char* a3 = a2 + kstep; const char* b3 = b2 + kstep;
;             if (last && has_next) S.a_ready(nxt);
;             if constexpr (SP2) {
;             PG8_LDB(B0, 0, 0); PG8_LDB(B1, 0, 1); PG8_SCHED; PG8_LDA(At, 0, 0); PG8_STAGE(PG8_SA(1, 1), a1 + hstepA, voffA);
;             PG8_WAIT_V(8); PG8_WAIT_L(0); PG8_BAR; PG8_MMA(0, 0, At, B0); PG8_MMA(0, 1, At, B1); PG8_BAR; PG8_SCHED;
;             PG8_LDA(At, 0, 1); PG8_STAGE(PG8_SB(0, 0), b2, voffB); PG8_STAGE(PG8_SB(0, 1), b2 + hstepB, voffB); PG8_STAGE(PG8_SA(0, 0), a2, voffA);
;     ...
;         for (int a = 0; a < 2; ++a)
; #pragma unroll
;             for (int b = 0; b < 2; ++b)
; #pragma unroll
;                 for (int m = 0; m < 4; ++m)
; #pragma unroll
;                     for (int n = 0; n < 2; ++n) acc[a][b][m][n] = AccT<I8>::zero();
;         cur = nxt; cA = nA; cB = nB; ++ui;
.LBB0_939:
	s_ashr_i32 s35, s34, 31
	s_lshl_b64 s[8:9], s[34:35], 20
	s_add_u32 s38, s47, s8
	s_addc_u32 s39, s74, s9
	s_and_b64 s[8:9], s[40:41], exec
	s_cselect_b32 s7, s39, s55
	s_cselect_b32 s35, s38, s54
	s_ashr_i32 s37, s36, 31
	s_lshl_b64 s[8:9], s[36:37], 20
	s_add_u32 s88, s73, s8
	s_addc_u32 s89, s75, s9
	s_and_b64 s[8:9], s[40:41], exec
	s_cselect_b32 s37, s89, s13
	s_cselect_b32 s49, s88, s12
	s_add_u32 s56, s12, 0x100
	s_addc_u32 s57, s13, 0
	s_add_u32 s8, s54, 0x80080
	v_mov_b32_e32 v0, 0
	s_addc_u32 s9, s55, 0
	s_mov_b32 s58, -2
	v_mov_b32_e32 v1, v0
	v_mov_b32_e32 v2, v0
	v_mov_b32_e32 v3, v0
	v_mov_b32_e32 v4, v0
	v_mov_b32_e32 v5, v0
	v_mov_b32_e32 v6, v0
	v_mov_b32_e32 v7, v0
	s_waitcnt vmcnt(0)
	v_mov_b32_e32 v16, v0
	v_mov_b32_e32 v17, v0
	v_mov_b32_e32 v18, v0
	v_mov_b32_e32 v19, v0
	v_mov_b32_e32 v20, v0
	v_mov_b32_e32 v21, v0
	v_mov_b32_e32 v22, v0
	v_mov_b32_e32 v23, v0
	v_mov_b32_e32 v32, v0
	v_mov_b32_e32 v33, v0
	v_mov_b32_e32 v34, v0
	v_mov_b32_e32 v35, v0
	v_mov_b32_e32 v36, v0
	v_mov_b32_e32 v37, v0
	v_mov_b32_e32 v38, v0
	v_mov_b32_e32 v39, v0
	v_mov_b32_e32 v48, v0
	v_mov_b32_e32 v49, v0
	v_mov_b32_e32 v50, v0
	v_mov_b32_e32 v51, v0
	v_mov_b32_e32 v52, v0
	v_mov_b32_e32 v53, v0
	v_mov_b32_e32 v54, v0
	v_mov_b32_e32 v55, v0
	v_mov_b32_e32 v8, v0
	v_mov_b32_e32 v9, v0
	v_mov_b32_e32 v10, v0
	v_mov_b32_e32 v11, v0
	v_mov_b32_e32 v12, v0
	v_mov_b32_e32 v13, v0
	v_mov_b32_e32 v14, v0
	v_mov_b32_e32 v15, v0
	v_mov_b32_e32 v24, v0
	v_mov_b32_e32 v25, v0
	v_mov_b32_e32 v26, v0
	v_mov_b32_e32 v27, v0
	v_mov_b32_e32 v28, v0
	v_mov_b32_e32 v29, v0
	v_mov_b32_e32 v30, v0
	v_mov_b32_e32 v31, v0
	v_mov_b32_e32 v40, v0
	v_mov_b32_e32 v41, v0
	v_mov_b32_e32 v42, v0
	v_mov_b32_e32 v43, v0
	v_mov_b32_e32 v44, v0
	v_mov_b32_e32 v45, v0
	v_mov_b32_e32 v46, v0
	v_mov_b32_e32 v47, v0
	v_mov_b32_e32 v56, v0
	v_mov_b32_e32 v57, v0
	v_mov_b32_e32 v58, v0
	v_mov_b32_e32 v59, v0
	v_mov_b32_e32 v60, v0
	v_mov_b32_e32 v61, v0
	v_mov_b32_e32 v62, v0
	v_mov_b32_e32 v63, v0
	v_mov_b32_e32 v64, v0
	v_mov_b32_e32 v65, v0
	v_mov_b32_e32 v66, v0
	v_mov_b32_e32 v67, v0
	v_mov_b32_e32 v68, v0
	v_mov_b32_e32 v69, v0
	v_mov_b32_e32 v70, v0
	v_mov_b32_e32 v71, v0
	v_mov_b32_e32 v80, v0
	v_mov_b32_e32 v81, v0
	v_mov_b32_e32 v82, v0
	v_mov_b32_e32 v83, v0
	v_mov_b32_e32 v84, v0
	v_mov_b32_e32 v85, v0
	v_mov_b32_e32 v86, v0
	v_mov_b32_e32 v87, v0
	v_mov_b32_e32 v98, v0
	v_mov_b32_e32 v99, v0
	v_mov_b32_e32 v100, v0
	v_mov_b32_e32 v101, v0
	v_mov_b32_e32 v102, v0
	v_mov_b32_e32 v103, v0
	v_mov_b32_e32 v104, v0
	v_mov_b32_e32 v105, v0
	v_mov_b32_e32 v114, v0
	v_mov_b32_e32 v115, v0
	v_mov_b32_e32 v116, v0
	v_mov_b32_e32 v117, v0
	v_mov_b32_e32 v118, v0
	v_mov_b32_e32 v119, v0
	v_mov_b32_e32 v120, v0
	v_mov_b32_e32 v121, v0
	v_mov_b32_e32 v72, v0
	v_mov_b32_e32 v73, v0
	v_mov_b32_e32 v74, v0
	v_mov_b32_e32 v75, v0
	v_mov_b32_e32 v76, v0
	v_mov_b32_e32 v77, v0
	v_mov_b32_e32 v78, v0
	v_mov_b32_e32 v79, v0
	v_mov_b32_e32 v88, v0
	v_mov_b32_e32 v89, v0
	v_mov_b32_e32 v90, v0
	v_mov_b32_e32 v91, v0
	v_mov_b32_e32 v92, v0
	v_mov_b32_e32 v93, v0
	v_mov_b32_e32 v94, v0
	v_mov_b32_e32 v95, v0
	v_mov_b32_e32 v106, v0
	v_mov_b32_e32 v107, v0
	v_mov_b32_e32 v108, v0
	v_mov_b32_e32 v109, v0
	v_mov_b32_e32 v110, v0
	v_mov_b32_e32 v111, v0
	v_mov_b32_e32 v112, v0
	v_mov_b32_e32 v113, v0
	v_mov_b32_e32 v122, v0
	v_mov_b32_e32 v123, v0
	v_mov_b32_e32 v124, v0
	v_mov_b32_e32 v125, v0
	v_mov_b32_e32 v126, v0
	v_mov_b32_e32 v127, v0
	v_mov_b32_e32 v128, v0
	v_mov_b32_e32 v129, v0
	s_cmp_lg_u64 s[26:27], 0
	s_cbranch_scc1 .Lgprio_940
	s_setprio 1
.Lgprio_940:
.LBB0_940:
	s_add_u32 s12, s8, 0xfff80080
	s_addc_u32 s13, s9, -1
	s_add_i32 s59, 0, 0x10000
	s_cmp_eq_u32 s58, 28
	s_cselect_b32 s55, s7, s13
	s_cselect_b32 s54, s35, s12
	v_add_u32_e32 v96, s59, v225
	s_cselect_b32 s13, s37, s57
	s_cselect_b32 s12, s49, s56
	s_add_i32 s60, 0, 0x14000
	ds_read_b128 v[130:133], v96
	ds_read_b128 v[134:137], v96 offset:1024
	ds_read_b128 v[138:141], v96 offset:2048
	ds_read_b128 v[142:145], v96 offset:3072
	v_add_u32_e32 v96, s60, v225
	ds_read_b128 v[146:149], v96
	ds_read_b128 v[150:153], v96 offset:1024
	ds_read_b128 v[166:169], v96 offset:2048
	ds_read_b128 v[170:173], v96 offset:3072
	v_lshl_add_u64 v[194:195], s[8:9], 0, v[164:165]
	s_add_i32 m0, s3, 0xc000
	ds_read_b128 v[174:177], v226
	ds_read_b128 v[178:181], v226 offset:1024
	ds_read_b128 v[182:185], v226 offset:2048
	ds_read_b128 v[186:189], v226 offset:3072
	ds_read_b128 v[190:193], v226 offset:4096
	ds_read_b128 v[200:203], v226 offset:5120
	ds_read_b128 v[204:207], v226 offset:6144
	ds_read_b128 v[228:231], v226 offset:7168
	global_load_lds_dwordx4 v[194:195], off
	v_lshl_add_u64 v[194:195], s[8:9], 0, v[162:163]
	s_add_i32 m0, s3, 0xe000
	s_nop 0
	global_load_lds_dwordx4 v[194:195], off
	s_waitcnt vmcnt(8)
	s_waitcnt lgkmcnt(0)
	s_barrier
; #define PG8_STAGE(bufoff, gbase, voff) do { _Pragma("unroll") for (int _i = 0; _i < 2; ++_i) \
;         __builtin_amdgcn_global_load_lds((const unsigned*)((const char*)(gbase) + (voff)[_i]), (PG8_LAS unsigned*)(lds + (bufoff) + ldsw + _i * 8192), 16, 0, 0); } while (0)
; #define PG8_LDA(dst, b, h) do { _Pragma("unroll") for (int m = 0; m < 4; ++m) _Pragma("unroll") for (int k = 0; k < 2; ++k) dst[m][k] = *(const PG8_LAS bf16x8*)(lds + PG8_SA(b, h) + aoff + m * 2048 + k * 1024); } while (0)
; #define PG8_LDB(dst, b, h) do { _Pragma("unroll") for (int n = 0; n < 2; ++n) _Pragma("unroll") for (int k = 0; k < 2; ++k) dst[n][k] = *(const PG8_LAS bf16x8*)(lds + PG8_SB(b, h) + boff + n * 2048 + k * 1024); } while (0)
; #define PG8_MMA(ai, bj, At, Bt) do { __builtin_amdgcn_s_setprio(1); _Pragma("unroll") for (int m = 0; m < 4; ++m) _Pragma("unroll") for (int n = 0; n < 2; ++n) _Pragma("unroll") for (int k = 0; k < 2; ++k) \
;         mma1<I8>(acc[ai][bj][m][n], Bt[n][k], At[m][k]); __builtin_amdgcn_s_setprio(0); } while (0)
; #define PG8_WAIT_V(n) asm volatile("s_waitcnt vmcnt(" #n ")" ::: "memory")
; #define PG8_WAIT_L(n) asm volatile("s_waitcnt lgkmcnt(" #n ")" ::: "memory")
; #define PG8_BAR __builtin_amdgcn_s_barrier()
; #define PG8_SCHED __builtin_amdgcn_sched_barrier(0)
; template <class Epi, class Sched, bool ALIGN_EPI = false, bool SP2 = false, bool I8 = false>
; __device__ __forceinline__ void gemm_phase(PG8_LAS unsigned char* lds, const Gemm g, const Sched& S, const Epi& E, const int tid) {
;     ...
;             PG8_LDB(B0, 0, 0); PG8_LDB(B1, 0, 1); PG8_SCHED; PG8_LDA(At, 0, 0); PG8_STAGE(PG8_SA(1, 1), a1 + hstepA, voffA);
;             PG8_WAIT_V(8); PG8_WAIT_L(0); PG8_BAR; PG8_MMA(0, 0, At, B0); PG8_MMA(0, 1, At, B1); PG8_BAR; PG8_SCHED;
;             PG8_LDA(At, 0, 1); PG8_STAGE(PG8_SB(0, 0), b2, voffB); PG8_STAGE(PG8_SB(0, 1), b2 + hstepB, voffB); PG8_STAGE(PG8_SA(0, 0), a2, voffA);
;             PG8_WAIT_V(8); PG8_WAIT_L(0); PG8_BAR; PG8_MMA(1, 0, At, B0); PG8_MMA(1, 1, At, B1); PG8_BAR; PG8_SCHED;
	s_waitcnt lgkmcnt(0)
	v_mfma_i32_16x16x64_i8 v[126:129], v[130:133], v[174:177], v[126:129]
	v_mfma_i32_16x16x64_i8 v[122:125], v[138:141], v[174:177], v[122:125]
	v_mfma_i32_16x16x64_i8 v[110:113], v[130:133], v[182:185], v[110:113]
	v_mfma_i32_16x16x64_i8 v[106:109], v[138:141], v[182:185], v[106:109]
	v_mfma_i32_16x16x64_i8 v[92:95], v[130:133], v[190:193], v[92:95]
	v_mfma_i32_16x16x64_i8 v[88:91], v[138:141], v[190:193], v[88:91]
	v_mfma_i32_16x16x64_i8 v[76:79], v[130:133], v[204:207], v[76:79]
	v_mfma_i32_16x16x64_i8 v[72:75], v[138:141], v[204:207], v[72:75]
	v_mfma_i32_16x16x64_i8 v[126:129], v[134:137], v[178:181], v[126:129]
	v_mfma_i32_16x16x64_i8 v[122:125], v[142:145], v[178:181], v[122:125]
	v_mfma_i32_16x16x64_i8 v[110:113], v[134:137], v[186:189], v[110:113]
	v_mfma_i32_16x16x64_i8 v[106:109], v[142:145], v[186:189], v[106:109]
	v_mfma_i32_16x16x64_i8 v[92:95], v[134:137], v[200:203], v[92:95]
	v_mfma_i32_16x16x64_i8 v[88:91], v[142:145], v[200:203], v[88:91]
	v_mfma_i32_16x16x64_i8 v[76:79], v[134:137], v[228:231], v[76:79]
	v_mfma_i32_16x16x64_i8 v[72:75], v[142:145], v[228:231], v[72:75]
	v_mfma_i32_16x16x64_i8 v[118:121], v[146:149], v[174:177], v[118:121]
	v_mfma_i32_16x16x64_i8 v[114:117], v[166:169], v[174:177], v[114:117]
	v_mfma_i32_16x16x64_i8 v[102:105], v[146:149], v[182:185], v[102:105]
	v_mfma_i32_16x16x64_i8 v[98:101], v[166:169], v[182:185], v[98:101]
	v_mfma_i32_16x16x64_i8 v[84:87], v[146:149], v[190:193], v[84:87]
	v_mfma_i32_16x16x64_i8 v[80:83], v[166:169], v[190:193], v[80:83]
	v_mfma_i32_16x16x64_i8 v[68:71], v[146:149], v[204:207], v[68:71]
	v_mfma_i32_16x16x64_i8 v[64:67], v[166:169], v[204:207], v[64:67]
	v_mfma_i32_16x16x64_i8 v[118:121], v[150:153], v[178:181], v[118:121]
	v_mfma_i32_16x16x64_i8 v[114:117], v[170:173], v[178:181], v[114:117]
	v_mfma_i32_16x16x64_i8 v[102:105], v[150:153], v[186:189], v[102:105]
	v_mfma_i32_16x16x64_i8 v[98:101], v[170:173], v[186:189], v[98:101]
	v_mfma_i32_16x16x64_i8 v[84:87], v[150:153], v[200:203], v[84:87]
	v_mfma_i32_16x16x64_i8 v[80:83], v[170:173], v[200:203], v[80:83]
	v_mfma_i32_16x16x64_i8 v[68:71], v[150:153], v[228:231], v[68:71]
	v_mfma_i32_16x16x64_i8 v[64:67], v[170:173], v[228:231], v[64:67]
	s_barrier
	s_add_i32 s59, s59, s1
	v_lshl_add_u64 v[194:195], s[12:13], 0, v[156:157]
	s_mov_b32 m0, s59
	ds_read_b128 v[174:177], v226 offset:16384
	ds_read_b128 v[178:181], v226 offset:17408
	ds_read_b128 v[182:185], v226 offset:18432
	ds_read_b128 v[186:189], v226 offset:19456
	ds_read_b128 v[190:193], v226 offset:20480
	ds_read_b128 v[200:203], v226 offset:21504
	ds_read_b128 v[204:207], v226 offset:22528
	ds_read_b128 v[228:231], v226 offset:23552
	global_load_lds_dwordx4 v[194:195], off
	s_add_i32 m0, s59, 0x2000
	s_add_u32 s76, s12, 0x80000
	v_lshl_add_u64 v[208:209], s[12:13], 0, v[160:161]
	s_addc_u32 s77, s13, 0
	s_add_i32 s59, s60, s1
	global_load_lds_dwordx4 v[208:209], off
	v_lshl_add_u64 v[212:213], s[76:77], 0, v[156:157]
	s_mov_b32 m0, s59
	v_lshl_add_u64 v[216:217], s[54:55], 0, v[158:159]
	global_load_lds_dwordx4 v[212:213], off
	v_lshl_add_u64 v[212:213], s[76:77], 0, v[160:161]
	s_add_i32 m0, s59, 0x2000
	s_nop 0
	global_load_lds_dwordx4 v[212:213], off
	v_lshl_add_u64 v[212:213], s[54:55], 0, v[154:155]
	s_mov_b32 m0, s3
	s_nop 0
	global_load_lds_dwordx4 v[212:213], off
	s_mov_b32 m0, s19
	s_nop 0
	global_load_lds_dwordx4 v[216:217], off
	s_waitcnt vmcnt(8)
	s_waitcnt lgkmcnt(0)
	s_barrier
	s_waitcnt lgkmcnt(0)
	v_mfma_i32_16x16x64_i8 v[60:63], v[130:133], v[174:177], v[60:63]
	v_mfma_i32_16x16x64_i8 v[56:59], v[138:141], v[174:177], v[56:59]
	v_mfma_i32_16x16x64_i8 v[44:47], v[130:133], v[182:185], v[44:47]
	v_mfma_i32_16x16x64_i8 v[40:43], v[138:141], v[182:185], v[40:43]
	v_mfma_i32_16x16x64_i8 v[28:31], v[130:133], v[190:193], v[28:31]
	v_mfma_i32_16x16x64_i8 v[24:27], v[138:141], v[190:193], v[24:27]
	v_mfma_i32_16x16x64_i8 v[12:15], v[130:133], v[204:207], v[12:15]
	v_mfma_i32_16x16x64_i8 v[8:11], v[138:141], v[204:207], v[8:11]
	v_mfma_i32_16x16x64_i8 v[60:63], v[134:137], v[178:181], v[60:63]
	v_mfma_i32_16x16x64_i8 v[56:59], v[142:145], v[178:181], v[56:59]
	v_mfma_i32_16x16x64_i8 v[44:47], v[134:137], v[186:189], v[44:47]
	v_mfma_i32_16x16x64_i8 v[40:43], v[142:145], v[186:189], v[40:43]
	v_mfma_i32_16x16x64_i8 v[28:31], v[134:137], v[200:203], v[28:31]
	v_mfma_i32_16x16x64_i8 v[24:27], v[142:145], v[200:203], v[24:27]
	v_mfma_i32_16x16x64_i8 v[12:15], v[134:137], v[228:231], v[12:15]
	v_mfma_i32_16x16x64_i8 v[8:11], v[142:145], v[228:231], v[8:11]
	v_mfma_i32_16x16x64_i8 v[52:55], v[146:149], v[174:177], v[52:55]
	v_mfma_i32_16x16x64_i8 v[48:51], v[166:169], v[174:177], v[48:51]
	v_mfma_i32_16x16x64_i8 v[36:39], v[146:149], v[182:185], v[36:39]
	v_mfma_i32_16x16x64_i8 v[32:35], v[166:169], v[182:185], v[32:35]
	v_mfma_i32_16x16x64_i8 v[20:23], v[146:149], v[190:193], v[20:23]
	v_mfma_i32_16x16x64_i8 v[16:19], v[166:169], v[190:193], v[16:19]
	v_mfma_i32_16x16x64_i8 v[4:7], v[146:149], v[204:207], v[4:7]
	v_mfma_i32_16x16x64_i8 v[0:3], v[166:169], v[204:207], v[0:3]
	v_mfma_i32_16x16x64_i8 v[52:55], v[150:153], v[178:181], v[52:55]
	v_mfma_i32_16x16x64_i8 v[48:51], v[170:173], v[178:181], v[48:51]
	v_mfma_i32_16x16x64_i8 v[36:39], v[150:153], v[186:189], v[36:39]
	v_mfma_i32_16x16x64_i8 v[32:35], v[170:173], v[186:189], v[32:35]
	v_mfma_i32_16x16x64_i8 v[20:23], v[150:153], v[200:203], v[20:23]
	v_mfma_i32_16x16x64_i8 v[16:19], v[170:173], v[200:203], v[16:19]
	v_mfma_i32_16x16x64_i8 v[4:7], v[150:153], v[228:231], v[4:7]
	v_mfma_i32_16x16x64_i8 v[0:3], v[170:173], v[228:231], v[0:3]
	s_barrier
; #define PG8_STAGE(bufoff, gbase, voff) do { _Pragma("unroll") for (int _i = 0; _i < 2; ++_i) \
;         __builtin_amdgcn_global_load_lds((const unsigned*)((const char*)(gbase) + (voff)[_i]), (PG8_LAS unsigned*)(lds + (bufoff) + ldsw + _i * 8192), 16, 0, 0); } while (0)
; #define PG8_LDA(dst, b, h) do { _Pragma("unroll") for (int m = 0; m < 4; ++m) _Pragma("unroll") for (int k = 0; k < 2; ++k) dst[m][k] = *(const PG8_LAS bf16x8*)(lds + PG8_SA(b, h) + aoff + m * 2048 + k * 1024); } while (0)
; #define PG8_LDB(dst, b, h) do { _Pragma("unroll") for (int n = 0; n < 2; ++n) _Pragma("unroll") for (int k = 0; k < 2; ++k) dst[n][k] = *(const PG8_LAS bf16x8*)(lds + PG8_SB(b, h) + boff + n * 2048 + k * 1024); } while (0)
; #define PG8_MMA(ai, bj, At, Bt) do { __builtin_amdgcn_s_setprio(1); _Pragma("unroll") for (int m = 0; m < 4; ++m) _Pragma("unroll") for (int n = 0; n < 2; ++n) _Pragma("unroll") for (int k = 0; k < 2; ++k) \
;         mma1<I8>(acc[ai][bj][m][n], Bt[n][k], At[m][k]); __builtin_amdgcn_s_setprio(0); } while (0)
; #define PG8_WAIT_V(n) asm volatile("s_waitcnt vmcnt(" #n ")" ::: "memory")
; #define PG8_WAIT_L(n) asm volatile("s_waitcnt lgkmcnt(" #n ")" ::: "memory")
; #define PG8_BAR __builtin_amdgcn_s_barrier()
; #define PG8_SCHED __builtin_amdgcn_sched_barrier(0)
; template <class Epi, class Sched, bool ALIGN_EPI = false, bool SP2 = false, bool I8 = false>
; __device__ __forceinline__ void gemm_phase(PG8_LAS unsigned char* lds, const Gemm g, const Sched& S, const Epi& E, const int tid) {
;     ...
;             PG8_LDB(B0, 1, 0); PG8_LDB(B1, 1, 1); PG8_SCHED; PG8_LDA(At, 1, 0); PG8_STAGE(PG8_SA(0, 1), a2 + hstepA, voffA);
;             PG8_WAIT_V(8); PG8_WAIT_L(0); PG8_BAR; PG8_MMA(0, 0, At, B0); PG8_MMA(0, 1, At, B1); PG8_BAR; PG8_SCHED;
;             PG8_LDA(At, 1, 1); PG8_STAGE(PG8_SB(1, 0), b3, voffB); PG8_STAGE(PG8_SB(1, 1), b3 + hstepB, voffB); PG8_STAGE(PG8_SA(1, 0), a3, voffA);
;             PG8_WAIT_V(8); PG8_WAIT_L(0); PG8_BAR; PG8_MMA(1, 0, At, B0); PG8_MMA(1, 1, At, B1); PG8_BAR; PG8_SCHED;
;     ...
;         if constexpr (ALIGN_EPI) { if (wr == 0) PG8_BAR; }
	s_add_i32 s59, 0, 0x18000
	v_add_u32_e32 v96, s59, v225
	s_add_i32 s60, 0, 0x1c000
	ds_read_b128 v[130:133], v96
	ds_read_b128 v[134:137], v96 offset:1024
	ds_read_b128 v[138:141], v96 offset:2048
	ds_read_b128 v[142:145], v96 offset:3072
	v_add_u32_e32 v96, s60, v225
	ds_read_b128 v[146:149], v96
	ds_read_b128 v[150:153], v96 offset:1024
	ds_read_b128 v[166:169], v96 offset:2048
	ds_read_b128 v[170:173], v96 offset:3072
	s_add_u32 s54, s54, 0x80000
	s_addc_u32 s55, s55, 0
	s_mov_b32 m0, s48
	v_lshl_add_u64 v[232:233], s[54:55], 0, v[154:155]
	ds_read_b128 v[174:177], v226 offset:32768
	ds_read_b128 v[178:181], v226 offset:33792
	ds_read_b128 v[182:185], v226 offset:34816
	ds_read_b128 v[186:189], v226 offset:35840
	ds_read_b128 v[190:193], v226 offset:36864
	ds_read_b128 v[200:203], v226 offset:37888
	ds_read_b128 v[204:207], v226 offset:38912
	ds_read_b128 v[228:231], v226 offset:39936
	global_load_lds_dwordx4 v[232:233], off
	v_lshl_add_u64 v[232:233], s[54:55], 0, v[158:159]
	s_mov_b32 m0, s51
	s_nop 0
	global_load_lds_dwordx4 v[232:233], off
	s_waitcnt vmcnt(8)
	s_waitcnt lgkmcnt(0)
	s_barrier
	s_waitcnt lgkmcnt(0)
	v_mfma_i32_16x16x64_i8 v[126:129], v[130:133], v[174:177], v[126:129]
	v_mfma_i32_16x16x64_i8 v[122:125], v[138:141], v[174:177], v[122:125]
	v_mfma_i32_16x16x64_i8 v[110:113], v[130:133], v[182:185], v[110:113]
	v_mfma_i32_16x16x64_i8 v[106:109], v[138:141], v[182:185], v[106:109]
	v_mfma_i32_16x16x64_i8 v[92:95], v[130:133], v[190:193], v[92:95]
	v_mfma_i32_16x16x64_i8 v[88:91], v[138:141], v[190:193], v[88:91]
	v_mfma_i32_16x16x64_i8 v[76:79], v[130:133], v[204:207], v[76:79]
	v_mfma_i32_16x16x64_i8 v[72:75], v[138:141], v[204:207], v[72:75]
	v_mfma_i32_16x16x64_i8 v[126:129], v[134:137], v[178:181], v[126:129]
	v_mfma_i32_16x16x64_i8 v[122:125], v[142:145], v[178:181], v[122:125]
	v_mfma_i32_16x16x64_i8 v[110:113], v[134:137], v[186:189], v[110:113]
	v_mfma_i32_16x16x64_i8 v[106:109], v[142:145], v[186:189], v[106:109]
	v_mfma_i32_16x16x64_i8 v[92:95], v[134:137], v[200:203], v[92:95]
	v_mfma_i32_16x16x64_i8 v[88:91], v[142:145], v[200:203], v[88:91]
	v_mfma_i32_16x16x64_i8 v[76:79], v[134:137], v[228:231], v[76:79]
	v_mfma_i32_16x16x64_i8 v[72:75], v[142:145], v[228:231], v[72:75]
	v_mfma_i32_16x16x64_i8 v[118:121], v[146:149], v[174:177], v[118:121]
	v_mfma_i32_16x16x64_i8 v[114:117], v[166:169], v[174:177], v[114:117]
	v_mfma_i32_16x16x64_i8 v[102:105], v[146:149], v[182:185], v[102:105]
	v_mfma_i32_16x16x64_i8 v[98:101], v[166:169], v[182:185], v[98:101]
	v_mfma_i32_16x16x64_i8 v[84:87], v[146:149], v[190:193], v[84:87]
	v_mfma_i32_16x16x64_i8 v[80:83], v[166:169], v[190:193], v[80:83]
	v_mfma_i32_16x16x64_i8 v[68:71], v[146:149], v[204:207], v[68:71]
	v_mfma_i32_16x16x64_i8 v[64:67], v[166:169], v[204:207], v[64:67]
	v_mfma_i32_16x16x64_i8 v[118:121], v[150:153], v[178:181], v[118:121]
	v_mfma_i32_16x16x64_i8 v[114:117], v[170:173], v[178:181], v[114:117]
	v_mfma_i32_16x16x64_i8 v[102:105], v[150:153], v[186:189], v[102:105]
	v_mfma_i32_16x16x64_i8 v[98:101], v[170:173], v[186:189], v[98:101]
	v_mfma_i32_16x16x64_i8 v[84:87], v[150:153], v[200:203], v[84:87]
	v_mfma_i32_16x16x64_i8 v[80:83], v[170:173], v[200:203], v[80:83]
	v_mfma_i32_16x16x64_i8 v[68:71], v[150:153], v[228:231], v[68:71]
	v_mfma_i32_16x16x64_i8 v[64:67], v[170:173], v[228:231], v[64:67]
	s_barrier
	s_add_i32 s54, s59, s1
	v_lshl_add_u64 v[194:195], v[194:195], 0, s[42:43]
	s_mov_b32 m0, s54
	ds_read_b128 v[174:177], v226 offset:49152
	ds_read_b128 v[178:181], v226 offset:50176
	ds_read_b128 v[182:185], v226 offset:51200
	ds_read_b128 v[186:189], v226 offset:52224
	ds_read_b128 v[190:193], v226 offset:53248
	ds_read_b128 v[200:203], v226 offset:54272
	ds_read_b128 v[204:207], v226 offset:55296
	ds_read_b128 v[228:231], v226 offset:56320
	global_load_lds_dwordx4 v[194:195], off
	s_add_i32 m0, s54, 0x2000
	s_add_u32 s12, s12, 0x80080
	v_lshl_add_u64 v[194:195], v[208:209], 0, s[42:43]
	s_addc_u32 s13, s13, 0
	s_add_i32 s54, s60, s1
	global_load_lds_dwordx4 v[194:195], off
	v_lshl_add_u64 v[194:195], s[12:13], 0, v[156:157]
	s_mov_b32 m0, s54
	s_nop 0
	global_load_lds_dwordx4 v[194:195], off
	v_lshl_add_u64 v[194:195], s[12:13], 0, v[160:161]
	s_add_i32 m0, s54, 0x2000
	s_nop 0
	global_load_lds_dwordx4 v[194:195], off
	v_lshl_add_u64 v[194:195], v[212:213], 0, s[42:43]
	s_mov_b32 m0, s63
	s_nop 0
	global_load_lds_dwordx4 v[194:195], off
	v_lshl_add_u64 v[194:195], v[216:217], 0, s[42:43]
	s_mov_b32 m0, s66
	s_nop 0
	global_load_lds_dwordx4 v[194:195], off
	s_waitcnt vmcnt(8)
	s_waitcnt lgkmcnt(0)
	s_barrier
	s_waitcnt lgkmcnt(0)
	v_mfma_i32_16x16x64_i8 v[60:63], v[130:133], v[174:177], v[60:63]
	v_mfma_i32_16x16x64_i8 v[56:59], v[138:141], v[174:177], v[56:59]
	v_mfma_i32_16x16x64_i8 v[44:47], v[130:133], v[182:185], v[44:47]
	v_mfma_i32_16x16x64_i8 v[40:43], v[138:141], v[182:185], v[40:43]
	v_mfma_i32_16x16x64_i8 v[28:31], v[130:133], v[190:193], v[28:31]
	v_mfma_i32_16x16x64_i8 v[24:27], v[138:141], v[190:193], v[24:27]
	v_mfma_i32_16x16x64_i8 v[12:15], v[130:133], v[204:207], v[12:15]
	v_mfma_i32_16x16x64_i8 v[8:11], v[138:141], v[204:207], v[8:11]
	v_mfma_i32_16x16x64_i8 v[60:63], v[134:137], v[178:181], v[60:63]
	v_mfma_i32_16x16x64_i8 v[56:59], v[142:145], v[178:181], v[56:59]
	v_mfma_i32_16x16x64_i8 v[44:47], v[134:137], v[186:189], v[44:47]
	v_mfma_i32_16x16x64_i8 v[40:43], v[142:145], v[186:189], v[40:43]
	v_mfma_i32_16x16x64_i8 v[28:31], v[134:137], v[200:203], v[28:31]
	v_mfma_i32_16x16x64_i8 v[24:27], v[142:145], v[200:203], v[24:27]
	v_mfma_i32_16x16x64_i8 v[12:15], v[134:137], v[228:231], v[12:15]
	v_mfma_i32_16x16x64_i8 v[8:11], v[142:145], v[228:231], v[8:11]
	v_mfma_i32_16x16x64_i8 v[52:55], v[146:149], v[174:177], v[52:55]
	v_mfma_i32_16x16x64_i8 v[48:51], v[166:169], v[174:177], v[48:51]
	v_mfma_i32_16x16x64_i8 v[36:39], v[146:149], v[182:185], v[36:39]
	v_mfma_i32_16x16x64_i8 v[32:35], v[166:169], v[182:185], v[32:35]
	v_mfma_i32_16x16x64_i8 v[20:23], v[146:149], v[190:193], v[20:23]
	v_mfma_i32_16x16x64_i8 v[16:19], v[166:169], v[190:193], v[16:19]
	v_mfma_i32_16x16x64_i8 v[4:7], v[146:149], v[204:207], v[4:7]
	v_mfma_i32_16x16x64_i8 v[0:3], v[166:169], v[204:207], v[0:3]
	v_mfma_i32_16x16x64_i8 v[52:55], v[150:153], v[178:181], v[52:55]
	v_mfma_i32_16x16x64_i8 v[48:51], v[170:173], v[178:181], v[48:51]
	v_mfma_i32_16x16x64_i8 v[36:39], v[150:153], v[186:189], v[36:39]
	v_mfma_i32_16x16x64_i8 v[32:35], v[170:173], v[186:189], v[32:35]
	v_mfma_i32_16x16x64_i8 v[20:23], v[150:153], v[200:203], v[20:23]
	v_mfma_i32_16x16x64_i8 v[16:19], v[170:173], v[200:203], v[16:19]
	v_mfma_i32_16x16x64_i8 v[4:7], v[150:153], v[228:231], v[4:7]
	v_mfma_i32_16x16x64_i8 v[0:3], v[170:173], v[228:231], v[0:3]
	s_barrier
	s_add_i32 s58, s58, 2
	s_add_u32 s56, s56, 0x100
	s_addc_u32 s57, s57, 0
	s_add_u32 s8, s8, 0x100
	s_addc_u32 s9, s9, 0
	s_cmp_gt_u32 s58, 29
	s_cbranch_scc0 .LBB0_940
	s_setprio 0
	s_and_b64 vcc, exec, s[26:27]
	s_cbranch_vccz .LBB0_943
	s_barrier

; #define PG8_STAGE(bufoff, gbase, voff) do { _Pragma("unroll") for (int _i = 0; _i < 2; ++_i) \
;         __builtin_amdgcn_global_load_lds((const unsigned*)((const char*)(gbase) + (voff)[_i]), (PG8_LAS unsigned*)(lds + (bufoff) + ldsw + _i * 8192), 16, 0, 0); } while (0)
; #define PG8_LDA(dst, b, h) do { _Pragma("unroll") for (int m = 0; m < 4; ++m) _Pragma("unroll") for (int k = 0; k < 2; ++k) dst[m][k] = *(const PG8_LAS bf16x8*)(lds + PG8_SA(b, h) + aoff + m * 2048 + k * 1024); } while (0)
; #define PG8_LDB(dst, b, h) do { _Pragma("unroll") for (int n = 0; n < 2; ++n) _Pragma("unroll") for (int k = 0; k < 2; ++k) dst[n][k] = *(const PG8_LAS bf16x8*)(lds + PG8_SB(b, h) + boff + n * 2048 + k * 1024); } while (0)
; #define PG8_WAIT_V(n) asm volatile("s_waitcnt vmcnt(" #n ")" ::: "memory")
; template <class Epi, class Sched, bool ALIGN_EPI = false, bool SP2 = false, bool I8 = false>
; __device__ __forceinline__ void gemm_phase(PG8_LAS unsigned char* lds, const Gemm g, const Sched& S, const Epi& E, const int tid) {
;     ...
;         const bool has_next = S.next(ui + 1, nxt);
;         const char* nA = has_next ? (const char*)g.A + (size_t)nxt.pm * tstepA : cA; const char* nB = has_next ? (const char*)g.Bt + (size_t)nxt.pn * tstepB : cB;
;         for (int t = 0; t < nt; t += 2) {
;             const bool last = (t == nt - 2);
;             const char* a1 = cA + (size_t)(t + 1) * kstep;
;             const char* a2 = last ? nA : cA + (size_t)(t + 2) * kstep; const char* b2 = last ? nB : cB + (size_t)(t + 2) * kstep;
;             const char* a3 = a2 + kstep; const char* b3 = b2 + kstep;
;             if (last && has_next) S.a_ready(nxt);
;             if constexpr (SP2) {
;             PG8_LDB(B0, 0, 0); PG8_LDB(B1, 0, 1); PG8_SCHED; PG8_LDA(At, 0, 0); PG8_STAGE(PG8_SA(1, 1), a1 + hstepA, voffA);
;             PG8_WAIT_V(8); PG8_WAIT_L(0); PG8_BAR; PG8_MMA(0, 0, At, B0); PG8_MMA(0, 1, At, B1); PG8_BAR; PG8_SCHED;
;             PG8_LDA(At, 0, 1); PG8_STAGE(PG8_SB(0, 0), b2, voffB); PG8_STAGE(PG8_SB(0, 1), b2 + hstepB, voffB); PG8_STAGE(PG8_SA(0, 0), a2, voffA);
;     ...
;         for (int a = 0; a < 2; ++a)
; #pragma unroll
;             for (int b = 0; b < 2; ++b)
; #pragma unroll
;                 for (int m = 0; m < 4; ++m)
; #pragma unroll
;                     for (int n = 0; n < 2; ++n) acc[a][b][m][n] = AccT<I8>::zero();
;         cur = nxt; cA = nA; cB = nB; ++ui;
.LBB0_1008:
	s_ashr_i32 s91, s90, 31
	s_lshl_b64 s[12:13], s[90:91], 20
	s_add_u32 s94, s47, s12
	s_addc_u32 s95, s74, s13
	s_and_b64 s[12:13], s[96:97], exec
	s_cselect_b32 s11, s95, s9
	s_cselect_b32 s14, s94, s8
	s_ashr_i32 s41, s40, 31
	s_lshl_b64 s[12:13], s[40:41], 20
	s_add_u32 s36, s73, s12
	s_addc_u32 s37, s75, s13
	s_and_b64 s[12:13], s[96:97], exec
	s_cselect_b32 s15, s37, s7
	s_cselect_b32 s24, s36, s6
	s_add_u32 s25, s6, 0x100
	s_addc_u32 s41, s7, 0
	s_add_u32 s6, s8, 0x80080
	v_mov_b32_e32 v0, 0
	s_addc_u32 s7, s9, 0
	s_mov_b32 s49, -2
	v_mov_b32_e32 v1, v0
	v_mov_b32_e32 v2, v0
	v_mov_b32_e32 v3, v0
	v_mov_b32_e32 v4, v0
	v_mov_b32_e32 v5, v0
	v_mov_b32_e32 v6, v0
	v_mov_b32_e32 v7, v0
	s_waitcnt vmcnt(0)
	v_mov_b32_e32 v16, v0
	v_mov_b32_e32 v17, v0
	v_mov_b32_e32 v18, v0
	v_mov_b32_e32 v19, v0
	v_mov_b32_e32 v20, v0
	v_mov_b32_e32 v21, v0
	v_mov_b32_e32 v22, v0
	v_mov_b32_e32 v23, v0
	v_mov_b32_e32 v32, v0
	v_mov_b32_e32 v33, v0
	v_mov_b32_e32 v34, v0
	v_mov_b32_e32 v35, v0
	v_mov_b32_e32 v36, v0
	v_mov_b32_e32 v37, v0
	v_mov_b32_e32 v38, v0
	v_mov_b32_e32 v39, v0
	v_mov_b32_e32 v48, v0
	v_mov_b32_e32 v49, v0
	v_mov_b32_e32 v50, v0
	v_mov_b32_e32 v51, v0
	v_mov_b32_e32 v52, v0
	v_mov_b32_e32 v53, v0
	v_mov_b32_e32 v54, v0
	v_mov_b32_e32 v55, v0
	v_mov_b32_e32 v8, v0
	v_mov_b32_e32 v9, v0
	v_mov_b32_e32 v10, v0
	v_mov_b32_e32 v11, v0
	v_mov_b32_e32 v12, v0
	v_mov_b32_e32 v13, v0
	v_mov_b32_e32 v14, v0
	v_mov_b32_e32 v15, v0
	v_mov_b32_e32 v24, v0
	v_mov_b32_e32 v25, v0
	v_mov_b32_e32 v26, v0
	v_mov_b32_e32 v27, v0
	v_mov_b32_e32 v28, v0
	v_mov_b32_e32 v29, v0
	v_mov_b32_e32 v30, v0
	v_mov_b32_e32 v31, v0
	v_mov_b32_e32 v40, v0
	v_mov_b32_e32 v41, v0
	v_mov_b32_e32 v42, v0
	v_mov_b32_e32 v43, v0
	v_mov_b32_e32 v44, v0
	v_mov_b32_e32 v45, v0
	v_mov_b32_e32 v46, v0
	v_mov_b32_e32 v47, v0
	v_mov_b32_e32 v56, v0
	v_mov_b32_e32 v57, v0
	v_mov_b32_e32 v58, v0
	v_mov_b32_e32 v59, v0
	v_mov_b32_e32 v60, v0
	v_mov_b32_e32 v61, v0
	v_mov_b32_e32 v62, v0
	v_mov_b32_e32 v63, v0
	v_mov_b32_e32 v64, v0
	v_mov_b32_e32 v65, v0
	v_mov_b32_e32 v66, v0
	v_mov_b32_e32 v67, v0
	v_mov_b32_e32 v68, v0
	v_mov_b32_e32 v69, v0
	v_mov_b32_e32 v70, v0
	v_mov_b32_e32 v71, v0
	v_mov_b32_e32 v80, v0
	v_mov_b32_e32 v81, v0
	v_mov_b32_e32 v82, v0
	v_mov_b32_e32 v83, v0
	v_mov_b32_e32 v84, v0
	v_mov_b32_e32 v85, v0
	v_mov_b32_e32 v86, v0
	v_mov_b32_e32 v87, v0
	v_mov_b32_e32 v98, v0
	v_mov_b32_e32 v99, v0
	v_mov_b32_e32 v100, v0
	v_mov_b32_e32 v101, v0
	v_mov_b32_e32 v102, v0
	v_mov_b32_e32 v103, v0
	v_mov_b32_e32 v104, v0
	v_mov_b32_e32 v105, v0
	v_mov_b32_e32 v114, v0
	v_mov_b32_e32 v115, v0
	v_mov_b32_e32 v116, v0
	v_mov_b32_e32 v117, v0
	v_mov_b32_e32 v118, v0
	v_mov_b32_e32 v119, v0
	v_mov_b32_e32 v120, v0
	v_mov_b32_e32 v121, v0
	v_mov_b32_e32 v72, v0
	v_mov_b32_e32 v73, v0
	v_mov_b32_e32 v74, v0
	v_mov_b32_e32 v75, v0
	v_mov_b32_e32 v76, v0
	v_mov_b32_e32 v77, v0
	v_mov_b32_e32 v78, v0
	v_mov_b32_e32 v79, v0
	v_mov_b32_e32 v88, v0
	v_mov_b32_e32 v89, v0
	v_mov_b32_e32 v90, v0
	v_mov_b32_e32 v91, v0
	v_mov_b32_e32 v92, v0
	v_mov_b32_e32 v93, v0
	v_mov_b32_e32 v94, v0
	v_mov_b32_e32 v95, v0
	v_mov_b32_e32 v106, v0
	v_mov_b32_e32 v107, v0
	v_mov_b32_e32 v108, v0
	v_mov_b32_e32 v109, v0
	v_mov_b32_e32 v110, v0
	v_mov_b32_e32 v111, v0
	v_mov_b32_e32 v112, v0
	v_mov_b32_e32 v113, v0
	v_mov_b32_e32 v122, v0
	v_mov_b32_e32 v123, v0
	v_mov_b32_e32 v124, v0
	v_mov_b32_e32 v125, v0
	v_mov_b32_e32 v126, v0
	v_mov_b32_e32 v127, v0
	v_mov_b32_e32 v128, v0
	v_mov_b32_e32 v129, v0
	s_cmp_lg_u64 s[38:39], 0
	s_cbranch_scc1 .Lgprio_1009
	s_setprio 1
.Lgprio_1009:
.LBB0_1009:
	s_add_u32 s8, s6, 0xfff80080
	s_addc_u32 s9, s7, -1
	s_add_i32 s54, 0, 0x10000
	s_cmp_eq_u32 s49, 28
	s_cselect_b32 s13, s11, s9
	s_cselect_b32 s12, s14, s8
	v_add_u32_e32 v96, s54, v243
	s_cselect_b32 s9, s15, s41
	s_cselect_b32 s8, s24, s25
	s_add_i32 s56, 0, 0x14000
	ds_read_b128 v[130:133], v96
	ds_read_b128 v[134:137], v96 offset:1024
	ds_read_b128 v[138:141], v96 offset:2048
	ds_read_b128 v[142:145], v96 offset:3072
	v_add_u32_e32 v96, s56, v243
	ds_read_b128 v[150:153], v96
	ds_read_b128 v[162:165], v96 offset:1024
	ds_read_b128 v[166:169], v96 offset:2048
	ds_read_b128 v[170:173], v96 offset:3072
	v_lshl_add_u64 v[194:195], s[6:7], 0, v[148:149]
	s_add_i32 m0, s93, 0xc000
	ds_read_b128 v[174:177], v244
	ds_read_b128 v[178:181], v244 offset:1024
	ds_read_b128 v[182:185], v244 offset:2048
	ds_read_b128 v[186:189], v244 offset:3072
	ds_read_b128 v[190:193], v244 offset:4096
	ds_read_b128 v[200:203], v244 offset:5120
	ds_read_b128 v[204:207], v244 offset:6144
	ds_read_b128 v[208:211], v244 offset:7168
	global_load_lds_dwordx4 v[194:195], off
	v_lshl_add_u64 v[194:195], s[6:7], 0, v[146:147]
	s_add_i32 m0, s93, 0xe000
	s_nop 0
	global_load_lds_dwordx4 v[194:195], off
	s_waitcnt vmcnt(8)
	s_waitcnt lgkmcnt(0)
	s_barrier
; #define PG8_STAGE(bufoff, gbase, voff) do { _Pragma("unroll") for (int _i = 0; _i < 2; ++_i) \
;         __builtin_amdgcn_global_load_lds((const unsigned*)((const char*)(gbase) + (voff)[_i]), (PG8_LAS unsigned*)(lds + (bufoff) + ldsw + _i * 8192), 16, 0, 0); } while (0)
; #define PG8_LDA(dst, b, h) do { _Pragma("unroll") for (int m = 0; m < 4; ++m) _Pragma("unroll") for (int k = 0; k < 2; ++k) dst[m][k] = *(const PG8_LAS bf16x8*)(lds + PG8_SA(b, h) + aoff + m * 2048 + k * 1024); } while (0)
; #define PG8_LDB(dst, b, h) do { _Pragma("unroll") for (int n = 0; n < 2; ++n) _Pragma("unroll") for (int k = 0; k < 2; ++k) dst[n][k] = *(const PG8_LAS bf16x8*)(lds + PG8_SB(b, h) + boff + n * 2048 + k * 1024); } while (0)
; #define PG8_MMA(ai, bj, At, Bt) do { __builtin_amdgcn_s_setprio(1); _Pragma("unroll") for (int m = 0; m < 4; ++m) _Pragma("unroll") for (int n = 0; n < 2; ++n) _Pragma("unroll") for (int k = 0; k < 2; ++k) \
;         mma1<I8>(acc[ai][bj][m][n], Bt[n][k], At[m][k]); __builtin_amdgcn_s_setprio(0); } while (0)
; #define PG8_WAIT_V(n) asm volatile("s_waitcnt vmcnt(" #n ")" ::: "memory")
; #define PG8_WAIT_L(n) asm volatile("s_waitcnt lgkmcnt(" #n ")" ::: "memory")
; #define PG8_BAR __builtin_amdgcn_s_barrier()
; #define PG8_SCHED __builtin_amdgcn_sched_barrier(0)
; template <class Epi, class Sched, bool ALIGN_EPI = false, bool SP2 = false, bool I8 = false>
; __device__ __forceinline__ void gemm_phase(PG8_LAS unsigned char* lds, const Gemm g, const Sched& S, const Epi& E, const int tid) {
;     ...
;             PG8_LDB(B0, 0, 0); PG8_LDB(B1, 0, 1); PG8_SCHED; PG8_LDA(At, 0, 0); PG8_STAGE(PG8_SA(1, 1), a1 + hstepA, voffA);
;             PG8_WAIT_V(8); PG8_WAIT_L(0); PG8_BAR; PG8_MMA(0, 0, At, B0); PG8_MMA(0, 1, At, B1); PG8_BAR; PG8_SCHED;
;             PG8_LDA(At, 0, 1); PG8_STAGE(PG8_SB(0, 0), b2, voffB); PG8_STAGE(PG8_SB(0, 1), b2 + hstepB, voffB); PG8_STAGE(PG8_SA(0, 0), a2, voffA);
;             PG8_WAIT_V(8); PG8_WAIT_L(0); PG8_BAR; PG8_MMA(1, 0, At, B0); PG8_MMA(1, 1, At, B1); PG8_BAR; PG8_SCHED;
	s_waitcnt lgkmcnt(0)
	v_mfma_i32_16x16x64_i8 v[126:129], v[130:133], v[174:177], v[126:129]
	v_mfma_i32_16x16x64_i8 v[122:125], v[138:141], v[174:177], v[122:125]
	v_mfma_i32_16x16x64_i8 v[110:113], v[130:133], v[182:185], v[110:113]
	v_mfma_i32_16x16x64_i8 v[106:109], v[138:141], v[182:185], v[106:109]
	v_mfma_i32_16x16x64_i8 v[92:95], v[130:133], v[190:193], v[92:95]
	v_mfma_i32_16x16x64_i8 v[88:91], v[138:141], v[190:193], v[88:91]
	v_mfma_i32_16x16x64_i8 v[76:79], v[130:133], v[204:207], v[76:79]
	v_mfma_i32_16x16x64_i8 v[72:75], v[138:141], v[204:207], v[72:75]
	v_mfma_i32_16x16x64_i8 v[126:129], v[134:137], v[178:181], v[126:129]
	v_mfma_i32_16x16x64_i8 v[122:125], v[142:145], v[178:181], v[122:125]
	v_mfma_i32_16x16x64_i8 v[110:113], v[134:137], v[186:189], v[110:113]
	v_mfma_i32_16x16x64_i8 v[106:109], v[142:145], v[186:189], v[106:109]
	v_mfma_i32_16x16x64_i8 v[92:95], v[134:137], v[200:203], v[92:95]
	v_mfma_i32_16x16x64_i8 v[88:91], v[142:145], v[200:203], v[88:91]
	v_mfma_i32_16x16x64_i8 v[76:79], v[134:137], v[208:211], v[76:79]
	v_mfma_i32_16x16x64_i8 v[72:75], v[142:145], v[208:211], v[72:75]
	v_mfma_i32_16x16x64_i8 v[118:121], v[150:153], v[174:177], v[118:121]
	v_mfma_i32_16x16x64_i8 v[114:117], v[166:169], v[174:177], v[114:117]
	v_mfma_i32_16x16x64_i8 v[102:105], v[150:153], v[182:185], v[102:105]
	v_mfma_i32_16x16x64_i8 v[98:101], v[166:169], v[182:185], v[98:101]
	v_mfma_i32_16x16x64_i8 v[84:87], v[150:153], v[190:193], v[84:87]
	v_mfma_i32_16x16x64_i8 v[80:83], v[166:169], v[190:193], v[80:83]
	v_mfma_i32_16x16x64_i8 v[68:71], v[150:153], v[204:207], v[68:71]
	v_mfma_i32_16x16x64_i8 v[64:67], v[166:169], v[204:207], v[64:67]
	v_mfma_i32_16x16x64_i8 v[118:121], v[162:165], v[178:181], v[118:121]
	v_mfma_i32_16x16x64_i8 v[114:117], v[170:173], v[178:181], v[114:117]
	v_mfma_i32_16x16x64_i8 v[102:105], v[162:165], v[186:189], v[102:105]
	v_mfma_i32_16x16x64_i8 v[98:101], v[170:173], v[186:189], v[98:101]
	v_mfma_i32_16x16x64_i8 v[84:87], v[162:165], v[200:203], v[84:87]
	v_mfma_i32_16x16x64_i8 v[80:83], v[170:173], v[200:203], v[80:83]
	v_mfma_i32_16x16x64_i8 v[68:71], v[162:165], v[208:211], v[68:71]
	v_mfma_i32_16x16x64_i8 v[64:67], v[170:173], v[208:211], v[64:67]
	s_barrier
	s_add_i32 s54, s54, s19
	v_lshl_add_u64 v[194:195], s[8:9], 0, v[156:157]
	s_mov_b32 m0, s54
	ds_read_b128 v[174:177], v244 offset:16384
	ds_read_b128 v[178:181], v244 offset:17408
	ds_read_b128 v[182:185], v244 offset:18432
	ds_read_b128 v[186:189], v244 offset:19456
	ds_read_b128 v[190:193], v244 offset:20480
	ds_read_b128 v[200:203], v244 offset:21504
	ds_read_b128 v[204:207], v244 offset:22528
	ds_read_b128 v[208:211], v244 offset:23552
	global_load_lds_dwordx4 v[194:195], off
	s_add_i32 m0, s54, 0x2000
	s_add_u32 s54, s8, 0x80000
	v_lshl_add_u64 v[212:213], s[8:9], 0, v[160:161]
	s_addc_u32 s55, s9, 0
	s_add_i32 s56, s56, s19
	global_load_lds_dwordx4 v[212:213], off
	v_lshl_add_u64 v[214:215], s[54:55], 0, v[156:157]
	s_mov_b32 m0, s56
	v_lshl_add_u64 v[216:217], s[12:13], 0, v[158:159]
	global_load_lds_dwordx4 v[214:215], off
	v_lshl_add_u64 v[214:215], s[54:55], 0, v[160:161]
	s_add_i32 m0, s56, 0x2000
	s_nop 0
	global_load_lds_dwordx4 v[214:215], off
	v_lshl_add_u64 v[214:215], s[12:13], 0, v[154:155]
	s_mov_b32 m0, s93
	s_nop 0
	global_load_lds_dwordx4 v[214:215], off
	s_mov_b32 m0, s66
	s_nop 0
	global_load_lds_dwordx4 v[216:217], off
	s_waitcnt vmcnt(8)
	s_waitcnt lgkmcnt(0)
	s_barrier
	s_waitcnt lgkmcnt(0)
	v_mfma_i32_16x16x64_i8 v[60:63], v[130:133], v[174:177], v[60:63]
	v_mfma_i32_16x16x64_i8 v[56:59], v[138:141], v[174:177], v[56:59]
	v_mfma_i32_16x16x64_i8 v[44:47], v[130:133], v[182:185], v[44:47]
	v_mfma_i32_16x16x64_i8 v[40:43], v[138:141], v[182:185], v[40:43]
	v_mfma_i32_16x16x64_i8 v[28:31], v[130:133], v[190:193], v[28:31]
	v_mfma_i32_16x16x64_i8 v[24:27], v[138:141], v[190:193], v[24:27]
	v_mfma_i32_16x16x64_i8 v[12:15], v[130:133], v[204:207], v[12:15]
	v_mfma_i32_16x16x64_i8 v[8:11], v[138:141], v[204:207], v[8:11]
	v_mfma_i32_16x16x64_i8 v[60:63], v[134:137], v[178:181], v[60:63]
	v_mfma_i32_16x16x64_i8 v[56:59], v[142:145], v[178:181], v[56:59]
	v_mfma_i32_16x16x64_i8 v[44:47], v[134:137], v[186:189], v[44:47]
	v_mfma_i32_16x16x64_i8 v[40:43], v[142:145], v[186:189], v[40:43]
	v_mfma_i32_16x16x64_i8 v[28:31], v[134:137], v[200:203], v[28:31]
	v_mfma_i32_16x16x64_i8 v[24:27], v[142:145], v[200:203], v[24:27]
	v_mfma_i32_16x16x64_i8 v[12:15], v[134:137], v[208:211], v[12:15]
	v_mfma_i32_16x16x64_i8 v[8:11], v[142:145], v[208:211], v[8:11]
	v_mfma_i32_16x16x64_i8 v[52:55], v[150:153], v[174:177], v[52:55]
	v_mfma_i32_16x16x64_i8 v[48:51], v[166:169], v[174:177], v[48:51]
	v_mfma_i32_16x16x64_i8 v[36:39], v[150:153], v[182:185], v[36:39]
	v_mfma_i32_16x16x64_i8 v[32:35], v[166:169], v[182:185], v[32:35]
	v_mfma_i32_16x16x64_i8 v[20:23], v[150:153], v[190:193], v[20:23]
	v_mfma_i32_16x16x64_i8 v[16:19], v[166:169], v[190:193], v[16:19]
	v_mfma_i32_16x16x64_i8 v[4:7], v[150:153], v[204:207], v[4:7]
	v_mfma_i32_16x16x64_i8 v[0:3], v[166:169], v[204:207], v[0:3]
	v_mfma_i32_16x16x64_i8 v[52:55], v[162:165], v[178:181], v[52:55]
	v_mfma_i32_16x16x64_i8 v[48:51], v[170:173], v[178:181], v[48:51]
	v_mfma_i32_16x16x64_i8 v[36:39], v[162:165], v[186:189], v[36:39]
	v_mfma_i32_16x16x64_i8 v[32:35], v[170:173], v[186:189], v[32:35]
	v_mfma_i32_16x16x64_i8 v[20:23], v[162:165], v[200:203], v[20:23]
	v_mfma_i32_16x16x64_i8 v[16:19], v[170:173], v[200:203], v[16:19]
	v_mfma_i32_16x16x64_i8 v[4:7], v[162:165], v[208:211], v[4:7]
	v_mfma_i32_16x16x64_i8 v[0:3], v[170:173], v[208:211], v[0:3]
	s_barrier
; #define PG8_STAGE(bufoff, gbase, voff) do { _Pragma("unroll") for (int _i = 0; _i < 2; ++_i) \
;         __builtin_amdgcn_global_load_lds((const unsigned*)((const char*)(gbase) + (voff)[_i]), (PG8_LAS unsigned*)(lds + (bufoff) + ldsw + _i * 8192), 16, 0, 0); } while (0)
; #define PG8_LDA(dst, b, h) do { _Pragma("unroll") for (int m = 0; m < 4; ++m) _Pragma("unroll") for (int k = 0; k < 2; ++k) dst[m][k] = *(const PG8_LAS bf16x8*)(lds + PG8_SA(b, h) + aoff + m * 2048 + k * 1024); } while (0)
; #define PG8_LDB(dst, b, h) do { _Pragma("unroll") for (int n = 0; n < 2; ++n) _Pragma("unroll") for (int k = 0; k < 2; ++k) dst[n][k] = *(const PG8_LAS bf16x8*)(lds + PG8_SB(b, h) + boff + n * 2048 + k * 1024); } while (0)
; #define PG8_MMA(ai, bj, At, Bt) do { __builtin_amdgcn_s_setprio(1); _Pragma("unroll") for (int m = 0; m < 4; ++m) _Pragma("unroll") for (int n = 0; n < 2; ++n) _Pragma("unroll") for (int k = 0; k < 2; ++k) \
;         mma1<I8>(acc[ai][bj][m][n], Bt[n][k], At[m][k]); __builtin_amdgcn_s_setprio(0); } while (0)
; #define PG8_WAIT_V(n) asm volatile("s_waitcnt vmcnt(" #n ")" ::: "memory")
; #define PG8_WAIT_L(n) asm volatile("s_waitcnt lgkmcnt(" #n ")" ::: "memory")
; #define PG8_BAR __builtin_amdgcn_s_barrier()
; #define PG8_SCHED __builtin_amdgcn_sched_barrier(0)
; template <class Epi, class Sched, bool ALIGN_EPI = false, bool SP2 = false, bool I8 = false>
; __device__ __forceinline__ void gemm_phase(PG8_LAS unsigned char* lds, const Gemm g, const Sched& S, const Epi& E, const int tid) {
;     ...
;             PG8_LDB(B0, 1, 0); PG8_LDB(B1, 1, 1); PG8_SCHED; PG8_LDA(At, 1, 0); PG8_STAGE(PG8_SA(0, 1), a2 + hstepA, voffA);
;             PG8_WAIT_V(8); PG8_WAIT_L(0); PG8_BAR; PG8_MMA(0, 0, At, B0); PG8_MMA(0, 1, At, B1); PG8_BAR; PG8_SCHED;
;             PG8_LDA(At, 1, 1); PG8_STAGE(PG8_SB(1, 0), b3, voffB); PG8_STAGE(PG8_SB(1, 1), b3 + hstepB, voffB); PG8_STAGE(PG8_SA(1, 0), a3, voffA);
;             PG8_WAIT_V(8); PG8_WAIT_L(0); PG8_BAR; PG8_MMA(1, 0, At, B0); PG8_MMA(1, 1, At, B1); PG8_BAR; PG8_SCHED;
;     ...
;         if constexpr (ALIGN_EPI) { if (wr == 0) PG8_BAR; }
	s_add_i32 s54, 0, 0x18000
	v_add_u32_e32 v96, s54, v243
	s_add_i32 s55, 0, 0x1c000
	ds_read_b128 v[130:133], v96
	ds_read_b128 v[134:137], v96 offset:1024
	ds_read_b128 v[138:141], v96 offset:2048
	ds_read_b128 v[142:145], v96 offset:3072
	v_add_u32_e32 v96, s55, v243
	ds_read_b128 v[150:153], v96
	ds_read_b128 v[162:165], v96 offset:1024
	ds_read_b128 v[166:169], v96 offset:2048
	ds_read_b128 v[170:173], v96 offset:3072
	s_add_u32 s12, s12, 0x80000
	s_addc_u32 s13, s13, 0
	s_mov_b32 m0, s1
	v_lshl_add_u64 v[218:219], s[12:13], 0, v[154:155]
	ds_read_b128 v[174:177], v244 offset:32768
	ds_read_b128 v[178:181], v244 offset:33792
	ds_read_b128 v[182:185], v244 offset:34816
	ds_read_b128 v[186:189], v244 offset:35840
	ds_read_b128 v[190:193], v244 offset:36864
	ds_read_b128 v[200:203], v244 offset:37888
	ds_read_b128 v[204:207], v244 offset:38912
	ds_read_b128 v[208:211], v244 offset:39936
	global_load_lds_dwordx4 v[218:219], off
	v_lshl_add_u64 v[218:219], s[12:13], 0, v[158:159]
	s_mov_b32 m0, s52
	s_nop 0
	global_load_lds_dwordx4 v[218:219], off
	s_waitcnt vmcnt(8)
	s_waitcnt lgkmcnt(0)
	s_barrier
	s_waitcnt lgkmcnt(0)
	v_mfma_i32_16x16x64_i8 v[126:129], v[130:133], v[174:177], v[126:129]
	v_mfma_i32_16x16x64_i8 v[122:125], v[138:141], v[174:177], v[122:125]
	v_mfma_i32_16x16x64_i8 v[110:113], v[130:133], v[182:185], v[110:113]
	v_mfma_i32_16x16x64_i8 v[106:109], v[138:141], v[182:185], v[106:109]
	v_mfma_i32_16x16x64_i8 v[92:95], v[130:133], v[190:193], v[92:95]
	v_mfma_i32_16x16x64_i8 v[88:91], v[138:141], v[190:193], v[88:91]
	v_mfma_i32_16x16x64_i8 v[76:79], v[130:133], v[204:207], v[76:79]
	v_mfma_i32_16x16x64_i8 v[72:75], v[138:141], v[204:207], v[72:75]
	v_mfma_i32_16x16x64_i8 v[126:129], v[134:137], v[178:181], v[126:129]
	v_mfma_i32_16x16x64_i8 v[122:125], v[142:145], v[178:181], v[122:125]
	v_mfma_i32_16x16x64_i8 v[110:113], v[134:137], v[186:189], v[110:113]
	v_mfma_i32_16x16x64_i8 v[106:109], v[142:145], v[186:189], v[106:109]
	v_mfma_i32_16x16x64_i8 v[92:95], v[134:137], v[200:203], v[92:95]
	v_mfma_i32_16x16x64_i8 v[88:91], v[142:145], v[200:203], v[88:91]
	v_mfma_i32_16x16x64_i8 v[76:79], v[134:137], v[208:211], v[76:79]
	v_mfma_i32_16x16x64_i8 v[72:75], v[142:145], v[208:211], v[72:75]
	v_mfma_i32_16x16x64_i8 v[118:121], v[150:153], v[174:177], v[118:121]
	v_mfma_i32_16x16x64_i8 v[114:117], v[166:169], v[174:177], v[114:117]
	v_mfma_i32_16x16x64_i8 v[102:105], v[150:153], v[182:185], v[102:105]
	v_mfma_i32_16x16x64_i8 v[98:101], v[166:169], v[182:185], v[98:101]
	v_mfma_i32_16x16x64_i8 v[84:87], v[150:153], v[190:193], v[84:87]
	v_mfma_i32_16x16x64_i8 v[80:83], v[166:169], v[190:193], v[80:83]
	v_mfma_i32_16x16x64_i8 v[68:71], v[150:153], v[204:207], v[68:71]
	v_mfma_i32_16x16x64_i8 v[64:67], v[166:169], v[204:207], v[64:67]
	v_mfma_i32_16x16x64_i8 v[118:121], v[162:165], v[178:181], v[118:121]
	v_mfma_i32_16x16x64_i8 v[114:117], v[170:173], v[178:181], v[114:117]
	v_mfma_i32_16x16x64_i8 v[102:105], v[162:165], v[186:189], v[102:105]
	v_mfma_i32_16x16x64_i8 v[98:101], v[170:173], v[186:189], v[98:101]
	v_mfma_i32_16x16x64_i8 v[84:87], v[162:165], v[200:203], v[84:87]
	v_mfma_i32_16x16x64_i8 v[80:83], v[170:173], v[200:203], v[80:83]
	v_mfma_i32_16x16x64_i8 v[68:71], v[162:165], v[208:211], v[68:71]
	v_mfma_i32_16x16x64_i8 v[64:67], v[170:173], v[208:211], v[64:67]
	s_barrier
	s_add_i32 s12, s54, s19
	v_lshl_add_u64 v[194:195], v[194:195], 0, s[42:43]
	s_mov_b32 m0, s12
	ds_read_b128 v[174:177], v244 offset:49152
	ds_read_b128 v[178:181], v244 offset:50176
	ds_read_b128 v[182:185], v244 offset:51200
	ds_read_b128 v[186:189], v244 offset:52224
	ds_read_b128 v[190:193], v244 offset:53248
	ds_read_b128 v[200:203], v244 offset:54272
	ds_read_b128 v[204:207], v244 offset:55296
	ds_read_b128 v[208:211], v244 offset:56320
	global_load_lds_dwordx4 v[194:195], off
	s_add_i32 m0, s12, 0x2000
	s_add_u32 s8, s8, 0x80080
	v_lshl_add_u64 v[194:195], v[212:213], 0, s[42:43]
	s_addc_u32 s9, s9, 0
	s_add_i32 s12, s55, s19
	global_load_lds_dwordx4 v[194:195], off
	v_lshl_add_u64 v[194:195], s[8:9], 0, v[156:157]
	s_mov_b32 m0, s12
	s_nop 0
	global_load_lds_dwordx4 v[194:195], off
	v_lshl_add_u64 v[194:195], s[8:9], 0, v[160:161]
	s_add_i32 m0, s12, 0x2000
	s_nop 0
	global_load_lds_dwordx4 v[194:195], off
	v_lshl_add_u64 v[194:195], v[214:215], 0, s[42:43]
	s_mov_b32 m0, s63
	s_nop 0
	global_load_lds_dwordx4 v[194:195], off
	v_lshl_add_u64 v[194:195], v[216:217], 0, s[42:43]
	s_mov_b32 m0, s86
	s_nop 0
	global_load_lds_dwordx4 v[194:195], off
	s_waitcnt vmcnt(8)
	s_waitcnt lgkmcnt(0)
	s_barrier
	s_waitcnt lgkmcnt(0)
	v_mfma_i32_16x16x64_i8 v[60:63], v[130:133], v[174:177], v[60:63]
	v_mfma_i32_16x16x64_i8 v[56:59], v[138:141], v[174:177], v[56:59]
	v_mfma_i32_16x16x64_i8 v[44:47], v[130:133], v[182:185], v[44:47]
	v_mfma_i32_16x16x64_i8 v[40:43], v[138:141], v[182:185], v[40:43]
	v_mfma_i32_16x16x64_i8 v[28:31], v[130:133], v[190:193], v[28:31]
	v_mfma_i32_16x16x64_i8 v[24:27], v[138:141], v[190:193], v[24:27]
	v_mfma_i32_16x16x64_i8 v[12:15], v[130:133], v[204:207], v[12:15]
	v_mfma_i32_16x16x64_i8 v[8:11], v[138:141], v[204:207], v[8:11]
	v_mfma_i32_16x16x64_i8 v[60:63], v[134:137], v[178:181], v[60:63]
	v_mfma_i32_16x16x64_i8 v[56:59], v[142:145], v[178:181], v[56:59]
	v_mfma_i32_16x16x64_i8 v[44:47], v[134:137], v[186:189], v[44:47]
	v_mfma_i32_16x16x64_i8 v[40:43], v[142:145], v[186:189], v[40:43]
	v_mfma_i32_16x16x64_i8 v[28:31], v[134:137], v[200:203], v[28:31]
	v_mfma_i32_16x16x64_i8 v[24:27], v[142:145], v[200:203], v[24:27]
	v_mfma_i32_16x16x64_i8 v[12:15], v[134:137], v[208:211], v[12:15]
	v_mfma_i32_16x16x64_i8 v[8:11], v[142:145], v[208:211], v[8:11]
	v_mfma_i32_16x16x64_i8 v[52:55], v[150:153], v[174:177], v[52:55]
	v_mfma_i32_16x16x64_i8 v[48:51], v[166:169], v[174:177], v[48:51]
	v_mfma_i32_16x16x64_i8 v[36:39], v[150:153], v[182:185], v[36:39]
	v_mfma_i32_16x16x64_i8 v[32:35], v[166:169], v[182:185], v[32:35]
	v_mfma_i32_16x16x64_i8 v[20:23], v[150:153], v[190:193], v[20:23]
	v_mfma_i32_16x16x64_i8 v[16:19], v[166:169], v[190:193], v[16:19]
	v_mfma_i32_16x16x64_i8 v[4:7], v[150:153], v[204:207], v[4:7]
	v_mfma_i32_16x16x64_i8 v[0:3], v[166:169], v[204:207], v[0:3]
	v_mfma_i32_16x16x64_i8 v[52:55], v[162:165], v[178:181], v[52:55]
	v_mfma_i32_16x16x64_i8 v[48:51], v[170:173], v[178:181], v[48:51]
	v_mfma_i32_16x16x64_i8 v[36:39], v[162:165], v[186:189], v[36:39]
	v_mfma_i32_16x16x64_i8 v[32:35], v[170:173], v[186:189], v[32:35]
	v_mfma_i32_16x16x64_i8 v[20:23], v[162:165], v[200:203], v[20:23]
	v_mfma_i32_16x16x64_i8 v[16:19], v[170:173], v[200:203], v[16:19]
	v_mfma_i32_16x16x64_i8 v[4:7], v[162:165], v[208:211], v[4:7]
	v_mfma_i32_16x16x64_i8 v[0:3], v[170:173], v[208:211], v[0:3]
	s_barrier
	s_add_i32 s49, s49, 2
	s_add_u32 s25, s25, 0x100
	s_addc_u32 s41, s41, 0
	s_add_u32 s6, s6, 0x100
	s_addc_u32 s7, s7, 0
	s_cmp_gt_u32 s49, 29
	s_cbranch_scc0 .LBB0_1009
	s_setprio 0
	s_and_b64 vcc, exec, s[38:39]
	s_cbranch_vccz .LBB0_1012
	s_barrier
